# strategy 7 on the row phases R1/R2: xor-butterfly reductions use DPP adds (lane^1,2,4,8) and permlane swaps (lane^16,32) instead of ds_bpermute + lgkmcnt waits (48 levels)
# speedup vs baseline: 1.0068x; 1.0052x over previous
.LBB0_719:
	v_lshl_add_u64 v[82:83], s[96:97], 0, v[80:81]
	s_mov_b32 s2, 0x12000000
	v_add_co_u32_e32 v88, vcc, s2, v82
	s_mov_b32 s2, 0x12001000
	s_nop 0
	v_addc_co_u32_e32 v89, vcc, 0, v83, vcc
	v_add_co_u32_e32 v90, vcc, s2, v82
	v_lshl_add_u64 v[86:87], s[96:97], 0, v[78:79]
	s_nop 0
	v_addc_co_u32_e32 v91, vcc, 0, v83, vcc
	s_mov_b32 s2, 0x600000
	v_add_co_u32_e32 v96, vcc, s2, v86
	global_load_dwordx2 v[84:85], v[90:91], off offset:-4096 nt
	global_load_dwordx2 v[94:95], v[88:89], off offset:512 nt
	global_load_dwordx2 v[92:93], v[88:89], off offset:1024 nt
	global_load_dwordx2 v[98:99], v[88:89], off offset:1536 nt
	v_addc_co_u32_e32 v97, vcc, 0, v87, vcc
	global_load_dword v135, v[96:97], off
	global_load_dwordx2 v[86:87], v[88:89], off offset:2048 nt
	global_load_dwordx2 v[124:125], v[88:89], off offset:2560 nt
	global_load_dwordx2 v[110:111], v[88:89], off offset:3072 nt
	global_load_dwordx2 v[104:105], v[88:89], off offset:3584 nt
	global_load_dword v134, v[96:97], off offset:64
	global_load_dwordx2 v[128:129], v[90:91], off nt
	global_load_dwordx2 v[122:123], v[90:91], off offset:512 nt
	global_load_dwordx2 v[108:109], v[90:91], off offset:1024 nt
	global_load_dwordx2 v[102:103], v[90:91], off offset:1536 nt
	global_load_dword v89, v[96:97], off offset:128
	global_load_dwordx2 v[126:127], v[90:91], off offset:2048 nt
	global_load_dwordx2 v[120:121], v[90:91], off offset:2560 nt
	global_load_dwordx2 v[106:107], v[90:91], off offset:3072 nt
	global_load_dwordx2 v[100:101], v[90:91], off offset:3584 nt
	global_load_dword v88, v[96:97], off offset:192
	s_lshl_b64 s[8:9], s[0:1], 2
	s_mov_b32 s0, 0x358637bd
	v_lshl_add_u64 v[112:113], v[68:69], 0, s[8:9]
	s_waitcnt vmcnt(0)
	s_nop 1
	s_waitcnt lgkmcnt(0)
	v_add_f32_dpp v90, v134, v134 quad_perm:[1,0,3,2] row_mask:0xf bank_mask:0xf
	v_add_f32_dpp v91, v135, v135 quad_perm:[1,0,3,2] row_mask:0xf bank_mask:0xf
	s_nop 1
	s_waitcnt lgkmcnt(0)
	v_add_f32_dpp v90, v90, v90 quad_perm:[2,3,0,1] row_mask:0xf bank_mask:0xf
	v_add_f32_dpp v91, v91, v91 quad_perm:[2,3,0,1] row_mask:0xf bank_mask:0xf
	s_nop 1
	s_waitcnt lgkmcnt(0)
	v_add_f32_dpp v90, v90, v90 row_half_mirror row_mask:0xf bank_mask:0xf
	v_add_f32_dpp v91, v91, v91 row_half_mirror row_mask:0xf bank_mask:0xf
	s_nop 1
	s_waitcnt lgkmcnt(0)
	v_add_f32_dpp v90, v90, v90 row_mirror row_mask:0xf bank_mask:0xf
	v_add_f32_dpp v91, v91, v91 row_mirror row_mask:0xf bank_mask:0xf
	v_mov_b64_e32 v[96:97], s[0:1]
	v_pk_fma_f32 v[90:91], v[90:91], s[60:61], v[96:97] op_sel_hi:[1,0,0]
	s_nop 0
	v_mul_f32_e32 v0, 0x4b800000, v91
	v_cmp_gt_f32_e64 s[0:1], s40, v91
	v_cmp_gt_f32_e32 vcc, s40, v90
	s_nop 0
	v_cndmask_b32_e64 v0, v91, v0, s[0:1]
	v_rsq_f32_e32 v0, v0
	s_nop 0
	v_mul_f32_e32 v91, 0x45800000, v0
	v_cndmask_b32_e64 v114, v0, v91, s[0:1]
	v_mul_f32_e32 v0, 0x4b800000, v90
	v_cndmask_b32_e32 v0, v90, v0, vcc
	v_rsq_f32_e32 v0, v0
	s_nop 1
	v_mul_f32_e32 v90, 0x45800000, v0
	v_cndmask_b32_e32 v0, v0, v90, vcc
	s_waitcnt lgkmcnt(0)
	v_add_f32_dpp v88, v88, v88 quad_perm:[1,0,3,2] row_mask:0xf bank_mask:0xf
	v_add_f32_dpp v89, v89, v89 quad_perm:[1,0,3,2] row_mask:0xf bank_mask:0xf
	s_nop 1
	s_waitcnt lgkmcnt(0)
	v_add_f32_dpp v88, v88, v88 quad_perm:[2,3,0,1] row_mask:0xf bank_mask:0xf
	v_add_f32_dpp v89, v89, v89 quad_perm:[2,3,0,1] row_mask:0xf bank_mask:0xf
	s_nop 1
	s_waitcnt lgkmcnt(0)
	v_add_f32_dpp v88, v88, v88 row_half_mirror row_mask:0xf bank_mask:0xf
	v_add_f32_dpp v89, v89, v89 row_half_mirror row_mask:0xf bank_mask:0xf
	s_nop 1
	s_waitcnt lgkmcnt(0)
	v_add_f32_dpp v88, v88, v88 row_mirror row_mask:0xf bank_mask:0xf
	v_add_f32_dpp v89, v89, v89 row_mirror row_mask:0xf bank_mask:0xf
	s_nop 0
	v_pk_fma_f32 v[88:89], v[88:89], s[60:61], v[96:97] op_sel_hi:[1,0,0]
	s_nop 0
	v_mul_f32_e32 v90, 0x4b800000, v89
	v_cmp_gt_f32_e64 s[0:1], s40, v89
	v_cmp_gt_f32_e32 vcc, s40, v88
	s_nop 0
	v_cndmask_b32_e64 v89, v89, v90, s[0:1]
	v_rsq_f32_e32 v89, v89
	s_nop 0
	v_mul_f32_e32 v90, 0x45800000, v89
	v_cndmask_b32_e64 v118, v89, v90, s[0:1]
	v_mul_f32_e32 v89, 0x4b800000, v88
	v_cndmask_b32_e32 v88, v88, v89, vcc
	v_rsq_f32_e32 v88, v88
	s_nop 0
	v_mul_f32_e32 v89, 0x45800000, v88
	v_cndmask_b32_e32 v116, v88, v89, vcc
	global_load_dwordx4 v[88:91], v[70:71], off
	global_load_dwordx4 v[134:137], v[112:113], off
	s_waitcnt vmcnt(0)
	v_pk_mul_f32 v[134:135], v[88:89], v[134:135]
	v_lshlrev_b32_e32 v88, 16, v84
	v_and_b32_e32 v89, 0xffff0000, v84
	v_lshlrev_b32_e32 v84, 16, v85
	v_and_b32_e32 v85, 0xffff0000, v85
	v_pk_mul_f32 v[136:137], v[90:91], v[136:137]
	v_pk_mul_f32 v[84:85], v[114:115], v[84:85] op_sel_hi:[0,1]
	v_pk_mul_f32 v[88:89], v[114:115], v[88:89] op_sel_hi:[0,1]
	v_pk_fma_f32 v[88:89], v[88:89], v[134:135], v[50:51]
	v_pk_fma_f32 v[90:91], v[84:85], v[136:137], v[52:53]
	v_lshlrev_b32_e32 v50, 16, v86
	v_and_b32_e32 v51, 0xffff0000, v86
	v_lshlrev_b32_e32 v52, 16, v87
	v_and_b32_e32 v53, 0xffff0000, v87
	v_pk_mul_f32 v[52:53], v[0:1], v[52:53] op_sel_hi:[0,1]
	v_pk_mul_f32 v[50:51], v[0:1], v[50:51] op_sel_hi:[0,1]
	v_pk_fma_f32 v[84:85], v[134:135], v[50:51], v[54:55]
	v_pk_fma_f32 v[86:87], v[136:137], v[52:53], v[56:57]
	v_lshlrev_b32_e32 v50, 16, v128
	v_and_b32_e32 v51, 0xffff0000, v128
	v_lshlrev_b32_e32 v52, 16, v129
	v_and_b32_e32 v53, 0xffff0000, v129
	v_pk_mul_f32 v[52:53], v[118:119], v[52:53] op_sel_hi:[0,1]
	v_pk_mul_f32 v[50:51], v[118:119], v[50:51] op_sel_hi:[0,1]
	v_pk_fma_f32 v[54:55], v[134:135], v[50:51], v[58:59]
	v_pk_fma_f32 v[56:57], v[136:137], v[52:53], v[60:61]
	v_lshlrev_b32_e32 v50, 16, v126
	v_and_b32_e32 v51, 0xffff0000, v126
	v_lshlrev_b32_e32 v52, 16, v127
	v_and_b32_e32 v53, 0xffff0000, v127
	v_pk_mul_f32 v[52:53], v[116:117], v[52:53] op_sel_hi:[0,1]
	v_pk_mul_f32 v[50:51], v[116:117], v[50:51] op_sel_hi:[0,1]
	v_pk_fma_f32 v[50:51], v[134:135], v[50:51], v[62:63]
	v_pk_fma_f32 v[52:53], v[136:137], v[52:53], v[64:65]
	global_load_dwordx4 v[58:61], v[70:71], off offset:1024
	global_load_dwordx4 v[62:65], v[112:113], off offset:1024
	s_waitcnt vmcnt(0)
	v_pk_mul_f32 v[126:127], v[60:61], v[64:65]
	v_pk_mul_f32 v[128:129], v[58:59], v[62:63]
	v_lshlrev_b32_e32 v58, 16, v94
	v_and_b32_e32 v59, 0xffff0000, v94
	v_lshlrev_b32_e32 v60, 16, v95
	v_and_b32_e32 v61, 0xffff0000, v95
	v_pk_mul_f32 v[60:61], v[114:115], v[60:61] op_sel_hi:[0,1]
	v_pk_mul_f32 v[58:59], v[114:115], v[58:59] op_sel_hi:[0,1]
	v_pk_fma_f32 v[62:63], v[58:59], v[128:129], v[34:35]
	v_pk_fma_f32 v[64:65], v[60:61], v[126:127], v[36:37]
	v_lshlrev_b32_e32 v34, 16, v124
	v_and_b32_e32 v35, 0xffff0000, v124
	v_lshlrev_b32_e32 v36, 16, v125
	v_and_b32_e32 v37, 0xffff0000, v125
	v_pk_mul_f32 v[36:37], v[0:1], v[36:37] op_sel_hi:[0,1]
	v_pk_mul_f32 v[34:35], v[0:1], v[34:35] op_sel_hi:[0,1]
	v_pk_fma_f32 v[58:59], v[34:35], v[128:129], v[38:39]
	v_pk_fma_f32 v[60:61], v[36:37], v[126:127], v[40:41]
	v_lshlrev_b32_e32 v34, 16, v122
	v_and_b32_e32 v35, 0xffff0000, v122
	v_lshlrev_b32_e32 v36, 16, v123
	v_and_b32_e32 v37, 0xffff0000, v123
	v_pk_mul_f32 v[36:37], v[118:119], v[36:37] op_sel_hi:[0,1]
	v_pk_mul_f32 v[34:35], v[118:119], v[34:35] op_sel_hi:[0,1]
	v_pk_fma_f32 v[38:39], v[128:129], v[34:35], v[42:43]
	v_pk_fma_f32 v[40:41], v[126:127], v[36:37], v[44:45]
	v_lshlrev_b32_e32 v34, 16, v120
	v_and_b32_e32 v35, 0xffff0000, v120
	v_lshlrev_b32_e32 v36, 16, v121
	v_and_b32_e32 v37, 0xffff0000, v121
	v_pk_mul_f32 v[36:37], v[116:117], v[36:37] op_sel_hi:[0,1]
	v_pk_mul_f32 v[34:35], v[116:117], v[34:35] op_sel_hi:[0,1]
	v_pk_fma_f32 v[34:35], v[128:129], v[34:35], v[46:47]
	v_pk_fma_f32 v[36:37], v[126:127], v[36:37], v[48:49]
	global_load_dwordx4 v[42:45], v[70:71], off offset:2048
	global_load_dwordx4 v[46:49], v[112:113], off offset:2048
	s_waitcnt vmcnt(0)
	v_pk_mul_f32 v[120:121], v[44:45], v[48:49]
	v_pk_mul_f32 v[122:123], v[42:43], v[46:47]
	v_lshlrev_b32_e32 v42, 16, v92
	v_and_b32_e32 v43, 0xffff0000, v92
	v_lshlrev_b32_e32 v44, 16, v93
	v_and_b32_e32 v45, 0xffff0000, v93
	v_pk_mul_f32 v[42:43], v[114:115], v[42:43] op_sel_hi:[0,1]
	v_pk_mul_f32 v[44:45], v[114:115], v[44:45] op_sel_hi:[0,1]
	v_pk_fma_f32 v[92:93], v[44:45], v[120:121], v[12:13]
	v_pk_fma_f32 v[94:95], v[42:43], v[122:123], v[10:11]
	v_lshlrev_b32_e32 v10, 16, v110
	v_and_b32_e32 v11, 0xffff0000, v110
	v_lshlrev_b32_e32 v12, 16, v111
	v_and_b32_e32 v13, 0xffff0000, v111
	v_pk_mul_f32 v[10:11], v[0:1], v[10:11] op_sel_hi:[0,1]
	v_pk_mul_f32 v[12:13], v[0:1], v[12:13] op_sel_hi:[0,1]
	v_pk_fma_f32 v[44:45], v[12:13], v[120:121], v[24:25]
	v_pk_fma_f32 v[48:49], v[10:11], v[122:123], v[22:23]
	v_lshlrev_b32_e32 v10, 16, v108
	v_and_b32_e32 v11, 0xffff0000, v108
	v_lshlrev_b32_e32 v12, 16, v109
	v_and_b32_e32 v13, 0xffff0000, v109
	v_pk_mul_f32 v[10:11], v[118:119], v[10:11] op_sel_hi:[0,1]
	v_pk_mul_f32 v[12:13], v[118:119], v[12:13] op_sel_hi:[0,1]
	v_pk_fma_f32 v[42:43], v[120:121], v[12:13], v[28:29]
	v_pk_fma_f32 v[46:47], v[122:123], v[10:11], v[26:27]
	v_lshlrev_b32_e32 v10, 16, v106
	v_and_b32_e32 v11, 0xffff0000, v106
	v_lshlrev_b32_e32 v12, 16, v107
	v_and_b32_e32 v13, 0xffff0000, v107
	v_pk_mul_f32 v[10:11], v[116:117], v[10:11] op_sel_hi:[0,1]
	v_pk_mul_f32 v[12:13], v[116:117], v[12:13] op_sel_hi:[0,1]
	v_pk_fma_f32 v[28:29], v[120:121], v[12:13], v[32:33]
	v_pk_fma_f32 v[30:31], v[122:123], v[10:11], v[30:31]
	global_load_dwordx4 v[10:13], v[70:71], off offset:3072
	global_load_dwordx4 v[22:25], v[112:113], off offset:3072
	s_waitcnt vmcnt(0)
	v_pk_mul_f32 v[32:33], v[10:11], v[22:23]
	v_lshlrev_b32_e32 v10, 16, v98
	v_and_b32_e32 v11, 0xffff0000, v98
	v_lshlrev_b32_e32 v22, 16, v99
	v_and_b32_e32 v23, 0xffff0000, v99
	v_pk_mul_f32 v[12:13], v[12:13], v[24:25]
	v_pk_mul_f32 v[10:11], v[114:115], v[10:11] op_sel_hi:[0,1]
	v_pk_mul_f32 v[22:23], v[114:115], v[22:23] op_sel_hi:[0,1]
	v_pk_fma_f32 v[24:25], v[22:23], v[12:13], v[4:5]
	v_pk_fma_f32 v[26:27], v[10:11], v[32:33], v[2:3]
	v_lshlrev_b32_e32 v2, 16, v104
	v_and_b32_e32 v3, 0xffff0000, v104
	v_lshlrev_b32_e32 v4, 16, v105
	v_and_b32_e32 v5, 0xffff0000, v105
	v_pk_mul_f32 v[2:3], v[0:1], v[2:3] op_sel_hi:[0,1]
	v_pk_mul_f32 v[4:5], v[0:1], v[4:5] op_sel_hi:[0,1]
	v_pk_fma_f32 v[10:11], v[4:5], v[12:13], v[8:9]
	v_pk_fma_f32 v[22:23], v[2:3], v[32:33], v[6:7]
	v_lshlrev_b32_e32 v2, 16, v102
	v_and_b32_e32 v3, 0xffff0000, v102
	v_lshlrev_b32_e32 v4, 16, v103
	v_and_b32_e32 v5, 0xffff0000, v103
	v_pk_mul_f32 v[2:3], v[118:119], v[2:3] op_sel_hi:[0,1]
	v_pk_mul_f32 v[4:5], v[118:119], v[4:5] op_sel_hi:[0,1]
	v_pk_fma_f32 v[8:9], v[4:5], v[12:13], v[16:17]
	v_pk_fma_f32 v[14:15], v[2:3], v[32:33], v[14:15]
	v_lshlrev_b32_e32 v2, 16, v100
	v_and_b32_e32 v3, 0xffff0000, v100
	v_lshlrev_b32_e32 v4, 16, v101
	v_and_b32_e32 v5, 0xffff0000, v101
	v_pk_mul_f32 v[2:3], v[116:117], v[2:3] op_sel_hi:[0,1]
	v_pk_mul_f32 v[4:5], v[116:117], v[4:5] op_sel_hi:[0,1]
	v_pk_fma_f32 v[6:7], v[12:13], v[4:5], v[20:21]
	v_pk_fma_f32 v[12:13], v[32:33], v[2:3], v[18:19]
	v_pk_mul_f32 v[2:3], v[90:91], v[90:91]
	v_pk_mul_f32 v[4:5], v[88:89], v[88:89]
	v_mul_f32_e32 v0, v26, v26
	v_pk_mov_b32 v[16:17], v[4:5], v[2:3] op_sel:[1,0]
	v_mov_b32_e32 v5, v3
	v_pk_add_f32 v[2:3], v[16:17], v[4:5]
	v_pk_mul_f32 v[4:5], v[64:65], v[64:65]
	v_pk_mul_f32 v[16:17], v[62:63], v[62:63]
	v_pk_add_f32 v[2:3], v[2:3], v[2:3] op_sel:[0,1] op_sel_hi:[1,0]
	v_pk_mov_b32 v[18:19], v[16:17], v[4:5] op_sel:[1,0]
	v_mov_b32_e32 v17, v5
	v_pk_add_f32 v[4:5], v[18:19], v[16:17]
	v_mul_f32_e32 v16, v27, v27
	v_pk_add_f32 v[4:5], v[4:5], v[4:5] op_sel:[0,1] op_sel_hi:[1,0]
	v_mov_b32_e32 v3, v0
	v_mov_b32_e32 v5, v16
	v_mul_f32_e32 v0, v95, v95
	v_mul_f32_e32 v17, v24, v24
	v_pk_add_f32 v[2:3], v[2:3], v[4:5]
	v_pk_fma_f32 v[4:5], v[94:95], v[94:95], v[0:1] op_sel_hi:[1,1,0]
	v_mul_f32_e32 v0, v93, v93
	v_mul_f32_e32 v18, v25, v25
	v_mov_b32_e32 v5, v17
	v_pk_fma_f32 v[16:17], v[92:93], v[92:93], v[0:1] op_sel_hi:[1,1,0]
	v_mul_f32_e32 v0, v22, v22
	v_mov_b32_e32 v17, v18
	v_pk_add_f32 v[4:5], v[4:5], v[16:17]
	v_pk_mul_f32 v[16:17], v[84:85], v[84:85]
	v_pk_add_f32 v[2:3], v[2:3], v[4:5]
	v_pk_mul_f32 v[4:5], v[86:87], v[86:87]
	s_nop 0
	v_pk_mov_b32 v[18:19], v[16:17], v[4:5] op_sel:[1,0]
	v_mov_b32_e32 v17, v5
	v_pk_add_f32 v[4:5], v[18:19], v[16:17]
	v_pk_mul_f32 v[16:17], v[60:61], v[60:61]
	v_pk_mul_f32 v[18:19], v[58:59], v[58:59]
	v_pk_add_f32 v[4:5], v[4:5], v[4:5] op_sel:[0,1] op_sel_hi:[1,0]
	v_pk_mov_b32 v[20:21], v[18:19], v[16:17] op_sel:[1,0]
	v_mov_b32_e32 v19, v17
	v_pk_add_f32 v[16:17], v[20:21], v[18:19]
	v_mul_f32_e32 v18, v23, v23
	v_pk_add_f32 v[16:17], v[16:17], v[16:17] op_sel:[0,1] op_sel_hi:[1,0]
	v_mov_b32_e32 v5, v0
	v_mov_b32_e32 v17, v18
	v_mul_f32_e32 v0, v49, v49
	v_mul_f32_e32 v19, v10, v10
	v_pk_add_f32 v[4:5], v[4:5], v[16:17]
	v_pk_fma_f32 v[16:17], v[48:49], v[48:49], v[0:1] op_sel_hi:[1,1,0]
	v_mul_f32_e32 v0, v45, v45
	v_mul_f32_e32 v20, v11, v11
	v_mov_b32_e32 v17, v19
	v_pk_fma_f32 v[18:19], v[44:45], v[44:45], v[0:1] op_sel_hi:[1,1,0]
	s_nop 0
	v_mov_b32_e32 v19, v20
	v_pk_add_f32 v[16:17], v[16:17], v[18:19]
	s_nop 0
	v_pk_add_f32 v[4:5], v[4:5], v[16:17]
	v_mov_b32_e32 v17, v2
	v_mov_b32_e32 v16, v4
	v_mov_b32_e32 v2, v5
	v_pk_add_f32 v[2:3], v[16:17], v[2:3]
	s_nop 1
	s_waitcnt lgkmcnt(0)
	v_add_f32_dpp v2, v2, v2 quad_perm:[1,0,3,2] row_mask:0xf bank_mask:0xf
	v_add_f32_dpp v3, v3, v3 quad_perm:[1,0,3,2] row_mask:0xf bank_mask:0xf
	s_nop 1
	s_waitcnt lgkmcnt(0)
	v_add_f32_dpp v2, v2, v2 quad_perm:[2,3,0,1] row_mask:0xf bank_mask:0xf
	v_add_f32_dpp v3, v3, v3 quad_perm:[2,3,0,1] row_mask:0xf bank_mask:0xf
	s_nop 1
	s_waitcnt lgkmcnt(0)
	v_add_f32_dpp v2, v2, v2 row_half_mirror row_mask:0xf bank_mask:0xf
	v_add_f32_dpp v3, v3, v3 row_half_mirror row_mask:0xf bank_mask:0xf
	s_nop 1
	s_waitcnt lgkmcnt(0)
	v_add_f32_dpp v2, v2, v2 row_mirror row_mask:0xf bank_mask:0xf
	v_add_f32_dpp v3, v3, v3 row_mirror row_mask:0xf bank_mask:0xf
	v_mov_b32_e32 v5, v3
	v_mov_b32_e32 v4, v2
	s_nop 1
	v_permlane16_swap_b32_e32 v5, v3
	v_permlane16_swap_b32_e32 v4, v2
	v_pk_add_f32 v[2:3], v[2:3], v[4:5]
	v_mov_b32_e32 v5, v3
	v_mov_b32_e32 v4, v2
	s_nop 1
	v_permlane32_swap_b32_e32 v5, v3
	v_permlane32_swap_b32_e32 v4, v2
	v_pk_add_f32 v[2:3], v[2:3], v[4:5]
	s_nop 0
	v_pk_fma_f32 v[2:3], v[2:3], s[60:61], v[96:97] op_sel_hi:[1,0,0]
	v_pk_mul_f32 v[4:5], v[54:55], v[54:55]
	v_mul_f32_e32 v0, 0x4b800000, v3
	v_cmp_gt_f32_e64 s[0:1], s40, v3
	v_cmp_gt_f32_e32 vcc, s40, v2
	s_nop 0
	v_cndmask_b32_e64 v0, v3, v0, s[0:1]
	v_rsq_f32_e32 v0, v0
	s_nop 0
	v_mul_f32_e32 v3, 0x45800000, v0
	v_cndmask_b32_e64 v16, v0, v3, s[0:1]
	v_mul_f32_e32 v0, 0x4b800000, v2
	v_cndmask_b32_e32 v0, v2, v0, vcc
	v_rsq_f32_e32 v0, v0
	v_pk_mul_f32 v[88:89], v[88:89], v[16:17] op_sel_hi:[1,0]
	v_pk_mul_f32 v[90:91], v[90:91], v[16:17] op_sel_hi:[1,0]
	v_pk_mul_f32 v[26:27], v[26:27], v[16:17] op_sel_hi:[1,0]
	v_mul_f32_e32 v2, 0x45800000, v0
	v_cndmask_b32_e32 v0, v0, v2, vcc
	v_pk_mul_f32 v[2:3], v[56:57], v[56:57]
	v_pk_mul_f32 v[84:85], v[84:85], v[0:1] op_sel_hi:[1,0]
	v_pk_mov_b32 v[18:19], v[4:5], v[2:3] op_sel:[1,0]
	v_mov_b32_e32 v5, v3
	v_pk_add_f32 v[2:3], v[18:19], v[4:5]
	v_pk_mul_f32 v[4:5], v[40:41], v[40:41]
	v_pk_add_f32 v[2:3], v[2:3], v[2:3] op_sel_hi:[0,1]
	v_pk_mul_f32 v[18:19], v[38:39], v[38:39]
	v_mul_f32_e32 v2, v46, v46
	v_pk_mov_b32 v[20:21], v[18:19], v[4:5] op_sel:[1,0]
	v_mov_b32_e32 v19, v5
	v_pk_add_f32 v[4:5], v[20:21], v[18:19]
	v_pk_fma_f32 v[18:19], v[46:47], v[46:47], v[2:3] op_sel_hi:[1,1,0]
	v_mul_f32_e32 v2, v42, v42
	v_pk_add_f32 v[4:5], v[4:5], v[4:5] op_sel_hi:[0,1]
	v_pk_fma_f32 v[20:21], v[42:43], v[42:43], v[2:3] op_sel_hi:[1,1,0]
	v_mul_f32_e32 v18, v14, v14
	v_mul_f32_e32 v20, v15, v15
	v_mul_f32_e32 v4, v8, v8
	v_mul_f32_e32 v2, v9, v9
	v_pk_add_f32 v[18:19], v[18:19], v[20:21]
	v_pk_add_f32 v[2:3], v[4:5], v[2:3]
	v_pk_mul_f32 v[4:5], v[52:53], v[52:53]
	v_pk_add_f32 v[2:3], v[18:19], v[2:3]
	v_pk_mul_f32 v[18:19], v[50:51], v[50:51]
	v_pk_mul_f32 v[86:87], v[86:87], v[0:1] op_sel_hi:[1,0]
	v_pk_mov_b32 v[20:21], v[18:19], v[4:5] op_sel:[1,0]
	v_mov_b32_e32 v19, v5
	v_pk_add_f32 v[4:5], v[20:21], v[18:19]
	v_pk_mul_f32 v[18:19], v[36:37], v[36:37]
	v_pk_add_f32 v[4:5], v[4:5], v[4:5] op_sel_hi:[0,1]
	v_pk_mul_f32 v[20:21], v[34:35], v[34:35]
	v_mul_f32_e32 v4, v30, v30
	v_pk_mov_b32 v[32:33], v[20:21], v[18:19] op_sel:[1,0]
	v_mov_b32_e32 v21, v19
	v_pk_add_f32 v[18:19], v[32:33], v[20:21]
	v_pk_fma_f32 v[20:21], v[30:31], v[30:31], v[4:5] op_sel_hi:[1,1,0]
	v_mul_f32_e32 v4, v28, v28
	v_pk_add_f32 v[18:19], v[18:19], v[18:19] op_sel_hi:[0,1]
	v_pk_fma_f32 v[32:33], v[28:29], v[28:29], v[4:5] op_sel_hi:[1,1,0]
	v_mul_f32_e32 v20, v12, v12
	v_mul_f32_e32 v32, v13, v13
	v_mul_f32_e32 v4, v6, v6
	v_mul_f32_e32 v18, v7, v7
	v_pk_add_f32 v[20:21], v[20:21], v[32:33]
	v_pk_add_f32 v[4:5], v[4:5], v[18:19]
	v_mov_b32_e32 v19, v2
	v_pk_add_f32 v[4:5], v[20:21], v[4:5]
	v_lshl_add_u64 v[32:33], v[72:73], 0, s[8:9]
	v_mov_b32_e32 v18, v4
	v_mov_b32_e32 v2, v5
	v_pk_add_f32 v[2:3], v[18:19], v[2:3]
	s_nop 1
	v_pk_mul_f32 v[10:11], v[10:11], v[0:1] op_sel_hi:[1,0]
	s_waitcnt lgkmcnt(0)
	v_add_f32_dpp v2, v2, v2 quad_perm:[1,0,3,2] row_mask:0xf bank_mask:0xf
	v_add_f32_dpp v3, v3, v3 quad_perm:[1,0,3,2] row_mask:0xf bank_mask:0xf
	s_nop 1
	s_waitcnt lgkmcnt(0)
	v_add_f32_dpp v2, v2, v2 quad_perm:[2,3,0,1] row_mask:0xf bank_mask:0xf
	v_add_f32_dpp v3, v3, v3 quad_perm:[2,3,0,1] row_mask:0xf bank_mask:0xf
	s_nop 1
	s_waitcnt lgkmcnt(0)
	v_add_f32_dpp v2, v2, v2 row_half_mirror row_mask:0xf bank_mask:0xf
	v_add_f32_dpp v3, v3, v3 row_half_mirror row_mask:0xf bank_mask:0xf
	s_nop 1
	s_waitcnt lgkmcnt(0)
	v_add_f32_dpp v2, v2, v2 row_mirror row_mask:0xf bank_mask:0xf
	v_add_f32_dpp v3, v3, v3 row_mirror row_mask:0xf bank_mask:0xf
	v_mov_b32_e32 v5, v3
	v_mov_b32_e32 v4, v2
	s_nop 1
	v_permlane16_swap_b32_e32 v5, v3
	v_permlane16_swap_b32_e32 v4, v2
	v_pk_add_f32 v[2:3], v[2:3], v[4:5]
	v_mov_b32_e32 v5, v3
	v_mov_b32_e32 v4, v2
	s_nop 1
	v_permlane32_swap_b32_e32 v5, v3
	v_permlane32_swap_b32_e32 v4, v2
	v_pk_add_f32 v[2:3], v[2:3], v[4:5]
	s_nop 0
	v_pk_fma_f32 v[2:3], v[2:3], s[60:61], v[96:97] op_sel_hi:[1,0,0]
	v_lshl_add_u64 v[96:97], v[74:75], 0, s[8:9]
	v_mul_f32_e32 v4, 0x4b800000, v3
	v_cmp_gt_f32_e64 s[0:1], s40, v3
	v_cmp_gt_f32_e32 vcc, s40, v2
	s_nop 0
	v_cndmask_b32_e64 v3, v3, v4, s[0:1]
	v_rsq_f32_e32 v3, v3
	s_nop 0
	v_mul_f32_e32 v4, 0x45800000, v3
	v_cndmask_b32_e64 v20, v3, v4, s[0:1]
	v_mul_f32_e32 v3, 0x4b800000, v2
	v_cndmask_b32_e32 v2, v2, v3, vcc
	v_rsq_f32_e32 v2, v2
	s_mov_b32 s0, 0x9000000
	v_pk_mul_f32 v[54:55], v[54:55], v[20:21] op_sel_hi:[1,0]
	v_pk_mul_f32 v[56:57], v[56:57], v[20:21] op_sel_hi:[1,0]
	v_mul_f32_e32 v3, 0x45800000, v2
	v_cndmask_b32_e32 v18, v2, v3, vcc
	global_load_dwordx4 v[2:5], v[76:77], off
	global_load_dwordx4 v[98:101], v[96:97], off
	v_pk_mul_f32 v[50:51], v[50:51], v[18:19] op_sel_hi:[1,0]
	v_pk_mul_f32 v[52:53], v[52:53], v[18:19] op_sel_hi:[1,0]
	v_pk_mul_f32 v[38:39], v[38:39], v[20:21] op_sel_hi:[1,0]
	v_pk_mul_f32 v[40:41], v[40:41], v[20:21] op_sel_hi:[1,0]
	v_pk_mul_f32 v[34:35], v[34:35], v[18:19] op_sel_hi:[1,0]
	v_pk_mul_f32 v[36:37], v[36:37], v[18:19] op_sel_hi:[1,0]
	v_pk_mul_f32 v[30:31], v[30:31], v[18:19] op_sel_hi:[1,0]
	v_pk_mul_f32 v[28:29], v[28:29], v[18:19] op_sel_hi:[1,0]
	v_pk_mul_f32 v[8:9], v[8:9], v[20:21] op_sel_hi:[1,0]
	v_pk_mul_f32 v[6:7], v[6:7], v[18:19] op_sel_hi:[1,0]
	s_waitcnt vmcnt(0)
	v_pk_add_f32 v[100:101], v[100:101], 1.0 op_sel_hi:[1,0]
	v_pk_add_f32 v[102:103], v[98:99], 1.0 op_sel_hi:[1,0]
	v_pk_mul_f32 v[98:99], v[4:5], v[100:101]
	v_pk_mul_f32 v[100:101], v[2:3], v[102:103]
	global_load_dwordx4 v[2:5], v[32:33], off
	s_waitcnt vmcnt(0)
	v_pk_fma_f32 v[88:89], v[88:89], v[100:101], v[2:3]
	s_nop 0
	v_cvt_pk_bf16_f32 v102, v88, v89
	v_add_co_u32_e32 v88, vcc, s0, v82
	s_mov_b32 s0, 0x9001000
	s_nop 0
	v_addc_co_u32_e32 v89, vcc, 0, v83, vcc
	v_pk_fma_f32 v[90:91], v[90:91], v[98:99], v[4:5]
	v_add_co_u32_e32 v82, vcc, s0, v82
	v_pk_fma_f32 v[86:87], v[86:87], v[98:99], v[4:5]
	v_pk_fma_f32 v[84:85], v[84:85], v[100:101], v[2:3]
	v_pk_fma_f32 v[56:57], v[98:99], v[56:57], v[4:5]
	v_pk_fma_f32 v[54:55], v[100:101], v[54:55], v[2:3]
	v_pk_fma_f32 v[4:5], v[98:99], v[52:53], v[4:5]
	v_pk_fma_f32 v[2:3], v[100:101], v[50:51], v[2:3]
	v_cvt_pk_bf16_f32 v103, v90, v91
	v_addc_co_u32_e32 v83, vcc, 0, v83, vcc
	v_cvt_pk_bf16_f32 v84, v84, v85
	v_cvt_pk_bf16_f32 v85, v86, v87
	v_cvt_pk_bf16_f32 v54, v54, v55
	v_cvt_pk_bf16_f32 v55, v56, v57
	v_cvt_pk_bf16_f32 v2, v2, v3
	v_cvt_pk_bf16_f32 v3, v4, v5
	global_store_dwordx2 v[82:83], v[102:103], off offset:-4096
	global_store_dwordx2 v[88:89], v[84:85], off offset:2048
	global_store_dwordx2 v[82:83], v[54:55], off
	global_store_dwordx2 v[82:83], v[2:3], off offset:2048
	global_load_dwordx4 v[2:5], v[76:77], off offset:1024
	s_nop 0
	global_load_dwordx4 v[50:53], v[96:97], off offset:1024
	v_pk_mul_f32 v[54:55], v[62:63], v[16:17] op_sel_hi:[1,0]
	v_pk_mul_f32 v[56:57], v[64:65], v[16:17] op_sel_hi:[1,0]
	v_readlane_b32 s0, v254, 38
	v_readlane_b32 s1, v254, 39
	s_add_i32 s6, s6, s0
	v_readlane_b32 s0, v254, 36
	v_readlane_b32 s1, v254, 37
	s_cmp_lt_i32 s6, s70
	s_waitcnt vmcnt(0)
	v_pk_add_f32 v[52:53], v[52:53], 1.0 op_sel_hi:[1,0]
	v_pk_add_f32 v[50:51], v[50:51], 1.0 op_sel_hi:[1,0]
	v_pk_mul_f32 v[52:53], v[4:5], v[52:53]
	v_pk_mul_f32 v[50:51], v[2:3], v[50:51]
	global_load_dwordx4 v[2:5], v[32:33], off offset:1024
	v_lshl_add_u64 v[78:79], v[78:79], 0, s[0:1]
	v_readlane_b32 s0, v254, 40
	v_readlane_b32 s1, v254, 41
	s_waitcnt vmcnt(0)
	v_pk_fma_f32 v[56:57], v[56:57], v[52:53], v[4:5]
	v_pk_fma_f32 v[54:55], v[54:55], v[50:51], v[2:3]
	v_pk_fma_f32 v[40:41], v[40:41], v[52:53], v[4:5]
	v_cvt_pk_bf16_f32 v54, v54, v55
	v_cvt_pk_bf16_f32 v55, v56, v57
	global_store_dwordx2 v[88:89], v[54:55], off offset:512
	v_pk_mul_f32 v[54:55], v[58:59], v[0:1] op_sel_hi:[1,0]
	v_pk_mul_f32 v[56:57], v[60:61], v[0:1] op_sel_hi:[1,0]
	v_pk_fma_f32 v[54:55], v[54:55], v[50:51], v[2:3]
	v_pk_fma_f32 v[56:57], v[56:57], v[52:53], v[4:5]
	v_pk_fma_f32 v[38:39], v[38:39], v[50:51], v[2:3]
	v_pk_fma_f32 v[4:5], v[52:53], v[36:37], v[4:5]
	v_pk_fma_f32 v[2:3], v[50:51], v[34:35], v[2:3]
	v_cvt_pk_bf16_f32 v54, v54, v55
	v_cvt_pk_bf16_f32 v55, v56, v57
	v_cvt_pk_bf16_f32 v38, v38, v39
	v_cvt_pk_bf16_f32 v39, v40, v41
	v_cvt_pk_bf16_f32 v2, v2, v3
	v_cvt_pk_bf16_f32 v3, v4, v5
	global_store_dwordx2 v[88:89], v[54:55], off offset:2560
	global_store_dwordx2 v[82:83], v[38:39], off offset:512
	global_store_dwordx2 v[82:83], v[2:3], off offset:2560
	global_load_dwordx4 v[2:5], v[76:77], off offset:2048
	s_nop 0
	global_load_dwordx4 v[34:37], v[96:97], off offset:2048
	v_pk_mul_f32 v[38:39], v[94:95], v[16:17] op_sel_hi:[1,0]
	v_pk_mul_f32 v[40:41], v[92:93], v[16:17] op_sel_hi:[1,0]
	v_pk_mul_f32 v[16:17], v[24:25], v[16:17] op_sel_hi:[1,0]
	v_lshl_add_u64 v[80:81], v[80:81], 0, s[0:1]
	s_waitcnt vmcnt(0)
	v_pk_add_f32 v[36:37], v[36:37], 1.0 op_sel_hi:[1,0]
	v_pk_add_f32 v[34:35], v[34:35], 1.0 op_sel_hi:[1,0]
	v_pk_mul_f32 v[36:37], v[4:5], v[36:37]
	v_pk_mul_f32 v[34:35], v[2:3], v[34:35]
	global_load_dwordx4 v[2:5], v[32:33], off offset:2048
	s_waitcnt vmcnt(0)
	v_pk_fma_f32 v[40:41], v[40:41], v[36:37], v[4:5]
	v_pk_fma_f32 v[38:39], v[38:39], v[34:35], v[2:3]
	s_nop 0
	v_cvt_pk_bf16_f32 v38, v38, v39
	v_cvt_pk_bf16_f32 v39, v40, v41
	global_store_dwordx2 v[88:89], v[38:39], off offset:1024
	v_pk_mul_f32 v[38:39], v[48:49], v[0:1] op_sel_hi:[1,0]
	v_pk_mul_f32 v[40:41], v[44:45], v[0:1] op_sel_hi:[1,0]
	v_pk_fma_f32 v[38:39], v[38:39], v[34:35], v[2:3]
	v_pk_fma_f32 v[40:41], v[40:41], v[36:37], v[4:5]
	v_cvt_pk_bf16_f32 v38, v38, v39
	v_cvt_pk_bf16_f32 v39, v40, v41
	global_store_dwordx2 v[88:89], v[38:39], off offset:3072
	v_pk_mul_f32 v[38:39], v[46:47], v[20:21] op_sel_hi:[1,0]
	v_pk_mul_f32 v[40:41], v[42:43], v[20:21] op_sel_hi:[1,0]
	v_pk_fma_f32 v[38:39], v[38:39], v[34:35], v[2:3]
	v_pk_fma_f32 v[40:41], v[40:41], v[36:37], v[4:5]
	v_pk_fma_f32 v[4:5], v[28:29], v[36:37], v[4:5]
	v_pk_fma_f32 v[2:3], v[30:31], v[34:35], v[2:3]
	v_cvt_pk_bf16_f32 v38, v38, v39
	v_cvt_pk_bf16_f32 v39, v40, v41
	v_cvt_pk_bf16_f32 v2, v2, v3
	v_cvt_pk_bf16_f32 v3, v4, v5
	global_store_dwordx2 v[82:83], v[38:39], off offset:1024
	global_store_dwordx2 v[82:83], v[2:3], off offset:3072
	global_load_dwordx4 v[2:5], v[76:77], off offset:3072
	s_nop 0
	global_load_dwordx4 v[28:31], v[96:97], off offset:3072
	s_waitcnt vmcnt(0)
	v_pk_add_f32 v[30:31], v[30:31], 1.0 op_sel_hi:[1,0]
	v_pk_add_f32 v[28:29], v[28:29], 1.0 op_sel_hi:[1,0]
	v_pk_mul_f32 v[30:31], v[4:5], v[30:31]
	v_pk_mul_f32 v[28:29], v[2:3], v[28:29]
	global_load_dwordx4 v[2:5], v[32:33], off offset:3072
	s_waitcnt vmcnt(0)
	v_pk_fma_f32 v[16:17], v[16:17], v[30:31], v[4:5]
	v_pk_fma_f32 v[24:25], v[26:27], v[28:29], v[2:3]
	v_pk_fma_f32 v[10:11], v[10:11], v[30:31], v[4:5]
	v_cvt_pk_bf16_f32 v24, v24, v25
	v_cvt_pk_bf16_f32 v25, v16, v17
	v_pk_mul_f32 v[16:17], v[22:23], v[0:1] op_sel_hi:[1,0]
	v_pk_fma_f32 v[8:9], v[8:9], v[30:31], v[4:5]
	v_pk_fma_f32 v[16:17], v[16:17], v[28:29], v[2:3]
	v_pk_fma_f32 v[4:5], v[6:7], v[30:31], v[4:5]
	v_cvt_pk_bf16_f32 v16, v16, v17
	v_cvt_pk_bf16_f32 v17, v10, v11
	v_pk_mul_f32 v[10:11], v[14:15], v[20:21] op_sel_hi:[1,0]
	global_store_dwordx2 v[88:89], v[24:25], off offset:1536
	v_pk_fma_f32 v[10:11], v[10:11], v[28:29], v[2:3]
	global_store_dwordx2 v[88:89], v[16:17], off offset:3584
	v_cvt_pk_bf16_f32 v10, v10, v11
	v_cvt_pk_bf16_f32 v11, v8, v9
	v_pk_mul_f32 v[8:9], v[12:13], v[18:19] op_sel_hi:[1,0]
	global_store_dwordx2 v[82:83], v[10:11], off offset:1536
	v_pk_fma_f32 v[2:3], v[8:9], v[28:29], v[2:3]
	s_nop 0
	v_cvt_pk_bf16_f32 v2, v2, v3
	v_cvt_pk_bf16_f32 v3, v4, v5
	global_store_dwordx2 v[82:83], v[2:3], off offset:3584
	s_cbranch_scc0 .LBB0_730

.LBB0_927:
	v_lshl_add_u64 v[90:91], s[96:97], 0, v[88:89]
	s_mov_b32 s2, 0x12000000
	v_add_co_u32_e32 v68, vcc, s2, v90
	s_mov_b32 s2, 0x12001000
	s_nop 0
	v_addc_co_u32_e32 v69, vcc, 0, v91, vcc
	v_add_co_u32_e32 v106, vcc, s2, v90
	v_lshl_add_u64 v[96:97], s[96:97], 0, v[86:87]
	s_nop 0
	v_addc_co_u32_e32 v107, vcc, 0, v91, vcc
	s_mov_b32 s2, 0x600000
	v_add_co_u32_e32 v108, vcc, s2, v96
	global_load_dwordx2 v[110:111], v[106:107], off offset:-4096 nt
	global_load_dwordx2 v[120:121], v[68:69], off offset:512 nt
	global_load_dwordx2 v[98:99], v[68:69], off offset:1024 nt
	global_load_dwordx2 v[66:67], v[68:69], off offset:1536 nt
	v_addc_co_u32_e32 v109, vcc, 0, v97, vcc
	global_load_dword v119, v[108:109], off
	global_load_dwordx2 v[112:113], v[68:69], off offset:2048 nt
	global_load_dwordx2 v[122:123], v[68:69], off offset:2560 nt
	global_load_dwordx2 v[104:105], v[68:69], off offset:3072 nt
	global_load_dwordx2 v[94:95], v[68:69], off offset:3584 nt
	global_load_dword v118, v[108:109], off offset:64
	global_load_dwordx2 v[114:115], v[106:107], off nt
	global_load_dwordx2 v[124:125], v[106:107], off offset:512 nt
	global_load_dwordx2 v[102:103], v[106:107], off offset:1024 nt
	global_load_dwordx2 v[92:93], v[106:107], off offset:1536 nt
	global_load_dword v129, v[108:109], off offset:128
	global_load_dwordx2 v[116:117], v[106:107], off offset:2048 nt
	global_load_dwordx2 v[126:127], v[106:107], off offset:2560 nt
	global_load_dwordx2 v[100:101], v[106:107], off offset:3072 nt
	global_load_dwordx2 v[68:69], v[106:107], off offset:3584 nt
	global_load_dword v128, v[108:109], off offset:192
	s_lshl_b64 s[4:5], s[0:1], 2
	s_mov_b32 s0, 0x358637bd
	v_lshl_add_u64 v[108:109], v[72:73], 0, s[4:5]
	s_waitcnt vmcnt(0)
	s_nop 1
	s_waitcnt lgkmcnt(0)
	v_add_f32_dpp v106, v118, v118 quad_perm:[1,0,3,2] row_mask:0xf bank_mask:0xf
	v_add_f32_dpp v107, v119, v119 quad_perm:[1,0,3,2] row_mask:0xf bank_mask:0xf
	s_nop 1
	s_waitcnt lgkmcnt(0)
	v_add_f32_dpp v106, v106, v106 quad_perm:[2,3,0,1] row_mask:0xf bank_mask:0xf
	v_add_f32_dpp v107, v107, v107 quad_perm:[2,3,0,1] row_mask:0xf bank_mask:0xf
	s_nop 1
	s_waitcnt lgkmcnt(0)
	v_add_f32_dpp v106, v106, v106 row_half_mirror row_mask:0xf bank_mask:0xf
	v_add_f32_dpp v107, v107, v107 row_half_mirror row_mask:0xf bank_mask:0xf
	s_nop 1
	s_waitcnt lgkmcnt(0)
	v_add_f32_dpp v118, v106, v106 row_mirror row_mask:0xf bank_mask:0xf
	v_add_f32_dpp v119, v107, v107 row_mirror row_mask:0xf bank_mask:0xf
	v_mov_b64_e32 v[106:107], s[0:1]
	v_pk_fma_f32 v[130:131], v[118:119], s[60:61], v[106:107] op_sel_hi:[1,0,0]
	s_nop 0
	v_mul_f32_e32 v0, 0x4b800000, v131
	v_cmp_gt_f32_e64 s[0:1], s40, v131
	v_cmp_gt_f32_e32 vcc, s40, v130
	s_nop 0
	v_cndmask_b32_e64 v0, v131, v0, s[0:1]
	v_rsq_f32_e32 v0, v0
	s_nop 1
	v_mul_f32_e32 v118, 0x45800000, v0
	v_cndmask_b32_e64 v118, v0, v118, s[0:1]
	v_mul_f32_e32 v0, 0x4b800000, v130
	v_cndmask_b32_e32 v0, v130, v0, vcc
	v_rsq_f32_e32 v0, v0
	s_waitcnt lgkmcnt(0)
	v_add_f32_dpp v128, v128, v128 quad_perm:[1,0,3,2] row_mask:0xf bank_mask:0xf
	v_add_f32_dpp v129, v129, v129 quad_perm:[1,0,3,2] row_mask:0xf bank_mask:0xf
	s_nop 1
	v_mul_f32_e32 v119, 0x45800000, v0
	v_cndmask_b32_e32 v0, v0, v119, vcc
	s_waitcnt lgkmcnt(0)
	v_add_f32_dpp v128, v128, v128 quad_perm:[2,3,0,1] row_mask:0xf bank_mask:0xf
	v_add_f32_dpp v129, v129, v129 quad_perm:[2,3,0,1] row_mask:0xf bank_mask:0xf
	s_nop 1
	s_waitcnt lgkmcnt(0)
	v_add_f32_dpp v128, v128, v128 row_half_mirror row_mask:0xf bank_mask:0xf
	v_add_f32_dpp v129, v129, v129 row_half_mirror row_mask:0xf bank_mask:0xf
	s_nop 1
	s_waitcnt lgkmcnt(0)
	v_add_f32_dpp v128, v128, v128 row_mirror row_mask:0xf bank_mask:0xf
	v_add_f32_dpp v129, v129, v129 row_mirror row_mask:0xf bank_mask:0xf
	s_nop 0
	v_pk_fma_f32 v[128:129], v[128:129], s[60:61], v[106:107] op_sel_hi:[1,0,0]
	s_nop 0
	v_mul_f32_e32 v119, 0x4b800000, v129
	v_cmp_gt_f32_e64 s[0:1], s40, v129
	v_cmp_gt_f32_e32 vcc, s40, v128
	s_nop 0
	v_cndmask_b32_e64 v119, v129, v119, s[0:1]
	v_rsq_f32_e32 v119, v119
	s_nop 0
	v_mul_f32_e32 v129, 0x45800000, v119
	v_cndmask_b32_e64 v150, v119, v129, s[0:1]
	v_mul_f32_e32 v119, 0x4b800000, v128
	v_cndmask_b32_e32 v119, v128, v119, vcc
	v_rsq_f32_e32 v119, v119
	s_mov_b32 s0, 0x36000000
	v_mul_f32_e32 v128, 0x45800000, v119
	v_cndmask_b32_e32 v148, v119, v128, vcc
	global_load_dwordx4 v[128:131], v[74:75], off
	global_load_dwordx4 v[132:135], v[108:109], off
	s_waitcnt vmcnt(0)
	v_pk_mul_f32 v[128:129], v[128:129], v[132:133]
	v_lshlrev_b32_e32 v132, 16, v110
	v_and_b32_e32 v133, 0xffff0000, v110
	v_lshlrev_b32_e32 v110, 16, v111
	v_and_b32_e32 v111, 0xffff0000, v111
	v_pk_mul_f32 v[130:131], v[130:131], v[134:135]
	v_pk_mul_f32 v[110:111], v[118:119], v[110:111] op_sel_hi:[0,1]
	v_pk_fma_f32 v[110:111], v[110:111], v[130:131], v[52:53]
	v_lshlrev_b32_e32 v52, 16, v112
	v_and_b32_e32 v53, 0xffff0000, v112
	v_lshlrev_b32_e32 v112, 16, v113
	v_and_b32_e32 v113, 0xffff0000, v113
	v_pk_mul_f32 v[112:113], v[0:1], v[112:113] op_sel_hi:[0,1]
	v_pk_mul_f32 v[52:53], v[0:1], v[52:53] op_sel_hi:[0,1]
	v_pk_fma_f32 v[52:53], v[128:129], v[52:53], v[54:55]
	v_pk_fma_f32 v[112:113], v[130:131], v[112:113], v[56:57]
	v_lshlrev_b32_e32 v54, 16, v114
	v_and_b32_e32 v55, 0xffff0000, v114
	v_lshlrev_b32_e32 v56, 16, v115
	v_and_b32_e32 v57, 0xffff0000, v115
	v_pk_mul_f32 v[56:57], v[150:151], v[56:57] op_sel_hi:[0,1]
	v_pk_mul_f32 v[54:55], v[150:151], v[54:55] op_sel_hi:[0,1]
	v_pk_fma_f32 v[54:55], v[128:129], v[54:55], v[58:59]
	v_pk_fma_f32 v[114:115], v[130:131], v[56:57], v[60:61]
	v_lshlrev_b32_e32 v56, 16, v116
	v_and_b32_e32 v57, 0xffff0000, v116
	v_lshlrev_b32_e32 v58, 16, v117
	v_and_b32_e32 v59, 0xffff0000, v117
	v_pk_mul_f32 v[58:59], v[148:149], v[58:59] op_sel_hi:[0,1]
	v_pk_mul_f32 v[56:57], v[148:149], v[56:57] op_sel_hi:[0,1]
	v_pk_fma_f32 v[56:57], v[128:129], v[56:57], v[62:63]
	v_pk_fma_f32 v[116:117], v[130:131], v[58:59], v[64:65]
	global_load_dwordx4 v[58:61], v[74:75], off offset:1024
	global_load_dwordx4 v[62:65], v[108:109], off offset:1024
	v_pk_mul_f32 v[132:133], v[118:119], v[132:133] op_sel_hi:[0,1]
	v_pk_fma_f32 v[50:51], v[132:133], v[128:129], v[50:51]
	s_waitcnt vmcnt(0)
	v_pk_mul_f32 v[60:61], v[60:61], v[64:65]
	v_pk_mul_f32 v[58:59], v[58:59], v[62:63]
	v_lshlrev_b32_e32 v62, 16, v120
	v_and_b32_e32 v63, 0xffff0000, v120
	v_lshlrev_b32_e32 v64, 16, v121
	v_and_b32_e32 v65, 0xffff0000, v121
	v_pk_mul_f32 v[64:65], v[118:119], v[64:65] op_sel_hi:[0,1]
	v_pk_mul_f32 v[62:63], v[118:119], v[62:63] op_sel_hi:[0,1]
	v_pk_fma_f32 v[120:121], v[62:63], v[58:59], v[34:35]
	v_pk_fma_f32 v[128:129], v[64:65], v[60:61], v[36:37]
	v_lshlrev_b32_e32 v34, 16, v122
	v_and_b32_e32 v35, 0xffff0000, v122
	v_lshlrev_b32_e32 v36, 16, v123
	v_and_b32_e32 v37, 0xffff0000, v123
	v_pk_mul_f32 v[36:37], v[0:1], v[36:37] op_sel_hi:[0,1]
	v_pk_mul_f32 v[34:35], v[0:1], v[34:35] op_sel_hi:[0,1]
	v_pk_fma_f32 v[122:123], v[34:35], v[58:59], v[38:39]
	v_pk_fma_f32 v[130:131], v[36:37], v[60:61], v[40:41]
	v_lshlrev_b32_e32 v34, 16, v124
	v_and_b32_e32 v35, 0xffff0000, v124
	v_lshlrev_b32_e32 v36, 16, v125
	v_and_b32_e32 v37, 0xffff0000, v125
	v_pk_mul_f32 v[36:37], v[150:151], v[36:37] op_sel_hi:[0,1]
	v_pk_mul_f32 v[34:35], v[150:151], v[34:35] op_sel_hi:[0,1]
	v_pk_fma_f32 v[124:125], v[58:59], v[34:35], v[42:43]
	v_pk_fma_f32 v[132:133], v[60:61], v[36:37], v[44:45]
	v_lshlrev_b32_e32 v34, 16, v126
	v_and_b32_e32 v35, 0xffff0000, v126
	v_lshlrev_b32_e32 v36, 16, v127
	v_and_b32_e32 v37, 0xffff0000, v127
	v_pk_mul_f32 v[36:37], v[148:149], v[36:37] op_sel_hi:[0,1]
	v_pk_mul_f32 v[34:35], v[148:149], v[34:35] op_sel_hi:[0,1]
	v_pk_fma_f32 v[126:127], v[58:59], v[34:35], v[46:47]
	v_pk_fma_f32 v[134:135], v[60:61], v[36:37], v[48:49]
	global_load_dwordx4 v[34:37], v[74:75], off offset:2048
	global_load_dwordx4 v[38:41], v[108:109], off offset:2048
	s_waitcnt vmcnt(0)
	v_pk_mul_f32 v[36:37], v[36:37], v[40:41]
	v_pk_mul_f32 v[34:35], v[34:35], v[38:39]
	v_lshlrev_b32_e32 v38, 16, v98
	v_and_b32_e32 v39, 0xffff0000, v98
	v_lshlrev_b32_e32 v40, 16, v99
	v_and_b32_e32 v41, 0xffff0000, v99
	v_pk_mul_f32 v[40:41], v[118:119], v[40:41] op_sel_hi:[0,1]
	v_pk_mul_f32 v[38:39], v[118:119], v[38:39] op_sel_hi:[0,1]
	v_pk_fma_f32 v[10:11], v[38:39], v[34:35], v[10:11]
	v_pk_fma_f32 v[12:13], v[40:41], v[36:37], v[12:13]
	v_lshlrev_b32_e32 v38, 16, v104
	v_and_b32_e32 v39, 0xffff0000, v104
	v_lshlrev_b32_e32 v40, 16, v105
	v_and_b32_e32 v41, 0xffff0000, v105
	v_pk_mul_f32 v[40:41], v[0:1], v[40:41] op_sel_hi:[0,1]
	v_pk_mul_f32 v[38:39], v[0:1], v[38:39] op_sel_hi:[0,1]
	v_pk_fma_f32 v[136:137], v[38:39], v[34:35], v[22:23]
	v_pk_fma_f32 v[142:143], v[40:41], v[36:37], v[24:25]
	v_lshlrev_b32_e32 v22, 16, v102
	v_and_b32_e32 v23, 0xffff0000, v102
	v_lshlrev_b32_e32 v24, 16, v103
	v_and_b32_e32 v25, 0xffff0000, v103
	v_pk_mul_f32 v[24:25], v[150:151], v[24:25] op_sel_hi:[0,1]
	v_pk_mul_f32 v[22:23], v[150:151], v[22:23] op_sel_hi:[0,1]
	v_pk_fma_f32 v[138:139], v[34:35], v[22:23], v[26:27]
	v_pk_fma_f32 v[144:145], v[36:37], v[24:25], v[28:29]
	v_lshlrev_b32_e32 v22, 16, v100
	v_and_b32_e32 v23, 0xffff0000, v100
	v_lshlrev_b32_e32 v24, 16, v101
	v_and_b32_e32 v25, 0xffff0000, v101
	v_pk_mul_f32 v[24:25], v[148:149], v[24:25] op_sel_hi:[0,1]
	v_pk_mul_f32 v[22:23], v[148:149], v[22:23] op_sel_hi:[0,1]
	v_pk_fma_f32 v[140:141], v[34:35], v[22:23], v[30:31]
	v_pk_fma_f32 v[146:147], v[36:37], v[24:25], v[32:33]
	global_load_dwordx4 v[22:25], v[74:75], off offset:3072
	global_load_dwordx4 v[26:29], v[108:109], off offset:3072
	s_waitcnt vmcnt(0)
	v_pk_mul_f32 v[22:23], v[22:23], v[26:27]
	v_lshlrev_b32_e32 v26, 16, v66
	v_and_b32_e32 v27, 0xffff0000, v66
	v_pk_mul_f32 v[26:27], v[118:119], v[26:27] op_sel_hi:[0,1]
	v_pk_mul_f32 v[24:25], v[24:25], v[28:29]
	v_lshlrev_b32_e32 v28, 16, v67
	v_and_b32_e32 v29, 0xffff0000, v67
	v_pk_fma_f32 v[62:63], v[26:27], v[22:23], v[2:3]
	v_lshlrev_b32_e32 v2, 16, v94
	v_and_b32_e32 v3, 0xffff0000, v94
	v_pk_mul_f32 v[28:29], v[118:119], v[28:29] op_sel_hi:[0,1]
	v_pk_mul_f32 v[2:3], v[0:1], v[2:3] op_sel_hi:[0,1]
	v_pk_fma_f32 v[64:65], v[28:29], v[24:25], v[4:5]
	v_lshlrev_b32_e32 v4, 16, v95
	v_and_b32_e32 v5, 0xffff0000, v95
	v_pk_fma_f32 v[58:59], v[2:3], v[22:23], v[6:7]
	v_lshlrev_b32_e32 v2, 16, v92
	v_and_b32_e32 v3, 0xffff0000, v92
	v_pk_mul_f32 v[4:5], v[0:1], v[4:5] op_sel_hi:[0,1]
	v_pk_mul_f32 v[2:3], v[150:151], v[2:3] op_sel_hi:[0,1]
	v_pk_fma_f32 v[60:61], v[4:5], v[24:25], v[8:9]
	v_lshlrev_b32_e32 v4, 16, v93
	v_and_b32_e32 v5, 0xffff0000, v93
	v_pk_fma_f32 v[92:93], v[2:3], v[22:23], v[14:15]
	v_lshlrev_b32_e32 v2, 16, v68
	v_and_b32_e32 v3, 0xffff0000, v68
	v_pk_mul_f32 v[2:3], v[148:149], v[2:3] op_sel_hi:[0,1]
	v_pk_fma_f32 v[66:67], v[22:23], v[2:3], v[18:19]
	v_add_co_u32_e32 v2, vcc, s0, v90
	s_mov_b32 s0, 0x36001000
	s_nop 0
	v_addc_co_u32_e32 v3, vcc, 0, v91, vcc
	v_add_co_u32_e32 v34, vcc, s0, v90
	v_pk_mul_f32 v[4:5], v[150:151], v[4:5] op_sel_hi:[0,1]
	s_nop 0
	v_addc_co_u32_e32 v35, vcc, 0, v91, vcc
	s_mov_b32 s0, 0xb00000
	v_pk_fma_f32 v[94:95], v[4:5], v[24:25], v[16:17]
	v_lshlrev_b32_e32 v4, 16, v69
	v_and_b32_e32 v5, 0xffff0000, v69
	v_add_co_u32_e32 v36, vcc, s0, v96
	v_pk_mul_f32 v[4:5], v[148:149], v[4:5] op_sel_hi:[0,1]
	s_nop 0
	v_addc_co_u32_e32 v37, vcc, 0, v97, vcc
	v_pk_fma_f32 v[68:69], v[24:25], v[4:5], v[20:21]
	global_load_dwordx2 v[26:27], v[34:35], off offset:-4096 nt
	global_load_dwordx2 v[18:19], v[2:3], off offset:512 nt
	global_load_dwordx2 v[6:7], v[2:3], off offset:1024 nt
	global_load_dwordx2 v[102:103], v[2:3], off offset:1536 nt
	global_load_dword v33, v[36:37], off
	global_load_dwordx2 v[28:29], v[2:3], off offset:2048 nt
	global_load_dwordx2 v[20:21], v[2:3], off offset:2560 nt
	global_load_dwordx2 v[8:9], v[2:3], off offset:3072 nt
	global_load_dwordx2 v[100:101], v[2:3], off offset:3584 nt
	global_load_dword v32, v[36:37], off offset:64
	global_load_dwordx2 v[24:25], v[34:35], off nt
	global_load_dwordx2 v[16:17], v[34:35], off offset:512 nt
	global_load_dwordx2 v[4:5], v[34:35], off offset:1024 nt
	global_load_dwordx2 v[98:99], v[34:35], off offset:1536 nt
	global_load_dword v31, v[36:37], off offset:128
	global_load_dwordx2 v[22:23], v[34:35], off offset:2048 nt
	global_load_dwordx2 v[14:15], v[34:35], off offset:2560 nt
	global_load_dwordx2 v[2:3], v[34:35], off offset:3072 nt
	global_load_dwordx2 v[96:97], v[34:35], off offset:3584 nt
	global_load_dword v30, v[36:37], off offset:192
	v_lshl_add_u64 v[118:119], v[76:77], 0, s[4:5]
	s_waitcnt vmcnt(15)
	s_nop 1
	s_waitcnt vmcnt(10)
	s_waitcnt lgkmcnt(0)
	v_add_f32_dpp v32, v32, v32 quad_perm:[1,0,3,2] row_mask:0xf bank_mask:0xf
	v_add_f32_dpp v33, v33, v33 quad_perm:[1,0,3,2] row_mask:0xf bank_mask:0xf
	s_nop 1
	s_waitcnt lgkmcnt(0)
	v_add_f32_dpp v32, v32, v32 quad_perm:[2,3,0,1] row_mask:0xf bank_mask:0xf
	v_add_f32_dpp v33, v33, v33 quad_perm:[2,3,0,1] row_mask:0xf bank_mask:0xf
	s_nop 1
	s_waitcnt lgkmcnt(0)
	v_add_f32_dpp v32, v32, v32 row_half_mirror row_mask:0xf bank_mask:0xf
	v_add_f32_dpp v33, v33, v33 row_half_mirror row_mask:0xf bank_mask:0xf
	s_nop 1
	s_waitcnt lgkmcnt(0)
	v_add_f32_dpp v32, v32, v32 row_mirror row_mask:0xf bank_mask:0xf
	v_add_f32_dpp v33, v33, v33 row_mirror row_mask:0xf bank_mask:0xf
	s_nop 0
	v_pk_fma_f32 v[32:33], v[32:33], s[60:61], v[106:107] op_sel_hi:[1,0,0]
	s_nop 0
	v_mul_f32_e32 v0, 0x4b800000, v33
	v_cmp_gt_f32_e64 s[0:1], s40, v33
	v_cmp_gt_f32_e32 vcc, s40, v32
	s_nop 0
	v_cndmask_b32_e64 v0, v33, v0, s[0:1]
	v_rsq_f32_e32 v0, v0
	s_nop 0
	v_mul_f32_e32 v33, 0x45800000, v0
	v_cndmask_b32_e64 v108, v0, v33, s[0:1]
	v_mul_f32_e32 v0, 0x4b800000, v32
	v_cndmask_b32_e32 v0, v32, v0, vcc
	v_rsq_f32_e32 v0, v0
	s_waitcnt vmcnt(5)
	s_nop 1
	v_mul_f32_e32 v32, 0x45800000, v0
	v_cndmask_b32_e32 v104, v0, v32, vcc
	s_waitcnt vmcnt(0)
	s_waitcnt lgkmcnt(0)
	v_add_f32_dpp v30, v30, v30 quad_perm:[1,0,3,2] row_mask:0xf bank_mask:0xf
	v_add_f32_dpp v31, v31, v31 quad_perm:[1,0,3,2] row_mask:0xf bank_mask:0xf
	s_nop 1
	s_waitcnt lgkmcnt(0)
	v_add_f32_dpp v30, v30, v30 quad_perm:[2,3,0,1] row_mask:0xf bank_mask:0xf
	v_add_f32_dpp v31, v31, v31 quad_perm:[2,3,0,1] row_mask:0xf bank_mask:0xf
	s_nop 1
	s_waitcnt lgkmcnt(0)
	v_add_f32_dpp v30, v30, v30 row_half_mirror row_mask:0xf bank_mask:0xf
	v_add_f32_dpp v31, v31, v31 row_half_mirror row_mask:0xf bank_mask:0xf
	s_nop 1
	s_waitcnt lgkmcnt(0)
	v_add_f32_dpp v30, v30, v30 row_mirror row_mask:0xf bank_mask:0xf
	v_add_f32_dpp v31, v31, v31 row_mirror row_mask:0xf bank_mask:0xf
	s_nop 0
	v_pk_fma_f32 v[30:31], v[30:31], s[60:61], v[106:107] op_sel_hi:[1,0,0]
	s_nop 0
	v_mul_f32_e32 v0, 0x4b800000, v31
	v_cmp_gt_f32_e64 s[0:1], s40, v31
	v_cmp_gt_f32_e32 vcc, s40, v30
	s_nop 0
	v_cndmask_b32_e64 v0, v31, v0, s[0:1]
	v_rsq_f32_e32 v0, v0
	s_nop 0
	v_mul_f32_e32 v31, 0x45800000, v0
	v_cndmask_b32_e64 v106, v0, v31, s[0:1]
	v_mul_f32_e32 v0, 0x4b800000, v30
	v_cndmask_b32_e32 v0, v30, v0, vcc
	v_rsq_f32_e32 v0, v0
	s_and_b64 s[0:1], s[8:9], exec
	v_readlane_b32 s0, v253, 0
	v_readlane_b32 s1, v253, 1
	v_mul_f32_e32 v30, 0x45800000, v0
	v_cndmask_b32_e32 v0, v0, v30, vcc
	global_load_dwordx4 v[30:33], v[78:79], off
	global_load_dwordx4 v[34:37], v[118:119], off
	v_readlane_b32 s2, v253, 2
	v_readlane_b32 s3, v253, 3
	v_readlane_b32 s0, v253, 61
	s_cselect_b32 s3, s3, s56
	s_cselect_b32 s2, s2, s0
	s_lshl_b64 s[0:1], s[10:11], 2
	s_add_u32 s2, s2, s0
	s_addc_u32 s3, s3, s1
	s_mov_b64 s[8:9], -1
	s_andn2_b64 vcc, exec, s[90:91]
	s_waitcnt vmcnt(0)
	v_pk_mul_f32 v[30:31], v[30:31], v[34:35]
	v_lshlrev_b32_e32 v34, 16, v26
	v_and_b32_e32 v35, 0xffff0000, v26
	v_lshlrev_b32_e32 v26, 16, v27
	v_and_b32_e32 v27, 0xffff0000, v27
	v_pk_mul_f32 v[32:33], v[32:33], v[36:37]
	v_pk_mul_f32 v[26:27], v[108:109], v[26:27] op_sel_hi:[0,1]
	v_pk_fma_f32 v[48:49], v[26:27], v[32:33], v[110:111]
	v_lshlrev_b32_e32 v26, 16, v28
	v_and_b32_e32 v27, 0xffff0000, v28
	v_pk_mul_f32 v[26:27], v[104:105], v[26:27] op_sel_hi:[0,1]
	v_pk_fma_f32 v[42:43], v[30:31], v[26:27], v[52:53]
	v_lshlrev_b32_e32 v26, 16, v24
	v_and_b32_e32 v27, 0xffff0000, v24
	v_lshlrev_b32_e32 v24, 16, v25
	v_and_b32_e32 v25, 0xffff0000, v25
	v_pk_mul_f32 v[24:25], v[106:107], v[24:25] op_sel_hi:[0,1]
	v_lshlrev_b32_e32 v28, 16, v29
	v_and_b32_e32 v29, 0xffff0000, v29
	v_pk_fma_f32 v[40:41], v[32:33], v[24:25], v[114:115]
	v_lshlrev_b32_e32 v24, 16, v22
	v_and_b32_e32 v25, 0xffff0000, v22
	v_lshlrev_b32_e32 v22, 16, v23
	v_and_b32_e32 v23, 0xffff0000, v23
	v_pk_mul_f32 v[34:35], v[108:109], v[34:35] op_sel_hi:[0,1]
	v_pk_mul_f32 v[28:29], v[104:105], v[28:29] op_sel_hi:[0,1]
	v_pk_mul_f32 v[26:27], v[106:107], v[26:27] op_sel_hi:[0,1]
	v_pk_mul_f32 v[24:25], v[0:1], v[24:25] op_sel_hi:[0,1]
	v_pk_mul_f32 v[22:23], v[0:1], v[22:23] op_sel_hi:[0,1]
	v_pk_fma_f32 v[46:47], v[34:35], v[30:31], v[50:51]
	v_pk_fma_f32 v[44:45], v[32:33], v[28:29], v[112:113]
	v_pk_fma_f32 v[38:39], v[30:31], v[26:27], v[54:55]
	v_pk_fma_f32 v[36:37], v[32:33], v[22:23], v[116:117]
	v_pk_fma_f32 v[34:35], v[30:31], v[24:25], v[56:57]
	global_load_dwordx4 v[22:25], v[78:79], off offset:1024
	global_load_dwordx4 v[26:29], v[118:119], off offset:1024
	s_waitcnt vmcnt(0)
	v_pk_mul_f32 v[52:53], v[22:23], v[26:27]
	v_lshlrev_b32_e32 v22, 16, v18
	v_and_b32_e32 v23, 0xffff0000, v18
	v_lshlrev_b32_e32 v18, 16, v19
	v_and_b32_e32 v19, 0xffff0000, v19
	v_pk_mul_f32 v[50:51], v[24:25], v[28:29]
	v_pk_mul_f32 v[18:19], v[108:109], v[18:19] op_sel_hi:[0,1]
	v_pk_fma_f32 v[32:33], v[18:19], v[50:51], v[128:129]
	v_lshlrev_b32_e32 v18, 16, v20
	v_and_b32_e32 v19, 0xffff0000, v20
	v_pk_mul_f32 v[18:19], v[104:105], v[18:19] op_sel_hi:[0,1]
	v_pk_fma_f32 v[26:27], v[18:19], v[52:53], v[122:123]
	v_lshlrev_b32_e32 v18, 16, v16
	v_and_b32_e32 v19, 0xffff0000, v16
	v_lshlrev_b32_e32 v16, 16, v17
	v_and_b32_e32 v17, 0xffff0000, v17
	v_pk_mul_f32 v[16:17], v[106:107], v[16:17] op_sel_hi:[0,1]
	v_lshlrev_b32_e32 v20, 16, v21
	v_and_b32_e32 v21, 0xffff0000, v21
	v_pk_fma_f32 v[24:25], v[50:51], v[16:17], v[132:133]
	v_lshlrev_b32_e32 v16, 16, v14
	v_and_b32_e32 v17, 0xffff0000, v14
	v_lshlrev_b32_e32 v14, 16, v15
	v_and_b32_e32 v15, 0xffff0000, v15
	v_pk_mul_f32 v[22:23], v[108:109], v[22:23] op_sel_hi:[0,1]
	v_pk_mul_f32 v[20:21], v[104:105], v[20:21] op_sel_hi:[0,1]
	v_pk_mul_f32 v[18:19], v[106:107], v[18:19] op_sel_hi:[0,1]
	v_pk_mul_f32 v[16:17], v[0:1], v[16:17] op_sel_hi:[0,1]
	v_pk_mul_f32 v[14:15], v[0:1], v[14:15] op_sel_hi:[0,1]
	v_pk_fma_f32 v[30:31], v[22:23], v[52:53], v[120:121]
	v_pk_fma_f32 v[28:29], v[20:21], v[50:51], v[130:131]
	v_pk_fma_f32 v[22:23], v[52:53], v[18:19], v[124:125]
	v_pk_fma_f32 v[20:21], v[50:51], v[14:15], v[134:135]
	v_pk_fma_f32 v[18:19], v[52:53], v[16:17], v[126:127]
	global_load_dwordx4 v[14:17], v[78:79], off offset:2048
	global_load_dwordx4 v[50:53], v[118:119], off offset:2048
	s_waitcnt vmcnt(0)
	v_pk_mul_f32 v[50:51], v[14:15], v[50:51]
	v_lshlrev_b32_e32 v14, 16, v6
	v_and_b32_e32 v15, 0xffff0000, v6
	v_lshlrev_b32_e32 v6, 16, v7
	v_and_b32_e32 v7, 0xffff0000, v7
	v_pk_mul_f32 v[52:53], v[16:17], v[52:53]
	v_pk_mul_f32 v[6:7], v[108:109], v[6:7] op_sel_hi:[0,1]
	v_pk_fma_f32 v[16:17], v[6:7], v[52:53], v[12:13]
	v_lshlrev_b32_e32 v6, 16, v8
	v_and_b32_e32 v7, 0xffff0000, v8
	v_pk_mul_f32 v[14:15], v[108:109], v[14:15] op_sel_hi:[0,1]
	v_pk_mul_f32 v[6:7], v[104:105], v[6:7] op_sel_hi:[0,1]
	v_pk_fma_f32 v[14:15], v[14:15], v[50:51], v[10:11]
	v_lshlrev_b32_e32 v8, 16, v9
	v_and_b32_e32 v9, 0xffff0000, v9
	v_pk_fma_f32 v[10:11], v[6:7], v[50:51], v[136:137]
	v_lshlrev_b32_e32 v6, 16, v4
	v_and_b32_e32 v7, 0xffff0000, v4
	v_lshlrev_b32_e32 v4, 16, v5
	v_and_b32_e32 v5, 0xffff0000, v5
	v_pk_mul_f32 v[8:9], v[104:105], v[8:9] op_sel_hi:[0,1]
	v_pk_mul_f32 v[4:5], v[106:107], v[4:5] op_sel_hi:[0,1]
	v_pk_fma_f32 v[12:13], v[8:9], v[52:53], v[142:143]
	v_pk_fma_f32 v[8:9], v[52:53], v[4:5], v[144:145]
	v_lshlrev_b32_e32 v4, 16, v2
	v_and_b32_e32 v5, 0xffff0000, v2
	v_lshlrev_b32_e32 v2, 16, v3
	v_and_b32_e32 v3, 0xffff0000, v3
	v_pk_mul_f32 v[6:7], v[106:107], v[6:7] op_sel_hi:[0,1]
	v_pk_mul_f32 v[54:55], v[0:1], v[4:5] op_sel_hi:[0,1]
	v_pk_mul_f32 v[2:3], v[0:1], v[2:3] op_sel_hi:[0,1]
	v_pk_fma_f32 v[6:7], v[50:51], v[6:7], v[138:139]
	v_pk_fma_f32 v[4:5], v[52:53], v[2:3], v[146:147]
	v_pk_fma_f32 v[2:3], v[50:51], v[54:55], v[140:141]
	global_load_dwordx4 v[50:53], v[78:79], off offset:3072
	global_load_dwordx4 v[54:57], v[118:119], off offset:3072
	s_waitcnt vmcnt(0)
	v_pk_mul_f32 v[52:53], v[52:53], v[56:57]
	v_pk_mul_f32 v[50:51], v[50:51], v[54:55]
	v_lshlrev_b32_e32 v54, 16, v102
	v_and_b32_e32 v55, 0xffff0000, v102
	v_lshlrev_b32_e32 v56, 16, v103
	v_and_b32_e32 v57, 0xffff0000, v103
	v_pk_mul_f32 v[54:55], v[108:109], v[54:55] op_sel_hi:[0,1]
	v_pk_mul_f32 v[56:57], v[108:109], v[56:57] op_sel_hi:[0,1]
	v_pk_fma_f32 v[64:65], v[56:57], v[52:53], v[64:65]
	v_pk_fma_f32 v[62:63], v[54:55], v[50:51], v[62:63]
	v_lshlrev_b32_e32 v54, 16, v100
	v_and_b32_e32 v55, 0xffff0000, v100
	v_lshlrev_b32_e32 v56, 16, v101
	v_and_b32_e32 v57, 0xffff0000, v101
	v_pk_mul_f32 v[54:55], v[104:105], v[54:55] op_sel_hi:[0,1]
	v_pk_mul_f32 v[56:57], v[104:105], v[56:57] op_sel_hi:[0,1]
	v_pk_fma_f32 v[60:61], v[56:57], v[52:53], v[60:61]
	v_pk_fma_f32 v[58:59], v[54:55], v[50:51], v[58:59]
	v_lshlrev_b32_e32 v54, 16, v98
	v_and_b32_e32 v55, 0xffff0000, v98
	v_lshlrev_b32_e32 v56, 16, v99
	v_and_b32_e32 v57, 0xffff0000, v99
	v_pk_mul_f32 v[54:55], v[106:107], v[54:55] op_sel_hi:[0,1]
	v_pk_mul_f32 v[56:57], v[106:107], v[56:57] op_sel_hi:[0,1]
	v_pk_fma_f32 v[56:57], v[56:57], v[52:53], v[94:95]
	v_pk_fma_f32 v[54:55], v[54:55], v[50:51], v[92:93]
	v_lshlrev_b32_e32 v92, 16, v96
	v_and_b32_e32 v93, 0xffff0000, v96
	v_lshlrev_b32_e32 v94, 16, v97
	v_and_b32_e32 v95, 0xffff0000, v97
	v_pk_mul_f32 v[92:93], v[0:1], v[92:93] op_sel_hi:[0,1]
	v_pk_mul_f32 v[94:95], v[0:1], v[94:95] op_sel_hi:[0,1]
	v_cndmask_b32_e64 v0, 0, 1, s[90:91]
	v_pk_fma_f32 v[52:53], v[52:53], v[94:95], v[68:69]
	v_pk_fma_f32 v[50:51], v[50:51], v[92:93], v[66:67]
	v_cmp_ne_u32_e64 s[0:1], 1, v0
	s_cbranch_vccz .LBB0_932
	s_andn2_b64 vcc, exec, s[8:9]
	s_cbranch_vccz .LBB0_933

.LBB0_934:
	v_pk_mul_f32 v[66:67], v[48:49], v[48:49]
	v_pk_mul_f32 v[68:69], v[46:47], v[46:47]
	v_mul_f32_e32 v0, v62, v62
	v_pk_mov_b32 v[92:93], v[68:69], v[66:67] op_sel:[1,0]
	v_mov_b32_e32 v69, v67
	v_pk_add_f32 v[66:67], v[92:93], v[68:69]
	v_pk_mul_f32 v[68:69], v[32:33], v[32:33]
	v_pk_mul_f32 v[92:93], v[30:31], v[30:31]
	v_pk_add_f32 v[66:67], v[66:67], v[66:67] op_sel:[0,1] op_sel_hi:[1,0]
	v_pk_mov_b32 v[94:95], v[92:93], v[68:69] op_sel:[1,0]
	v_mov_b32_e32 v93, v69
	v_pk_add_f32 v[68:69], v[94:95], v[92:93]
	v_mul_f32_e32 v92, v63, v63
	v_pk_add_f32 v[68:69], v[68:69], v[68:69] op_sel:[0,1] op_sel_hi:[1,0]
	v_mov_b32_e32 v67, v0
	v_mov_b32_e32 v69, v92
	v_mul_f32_e32 v0, v15, v15
	v_mul_f32_e32 v93, v64, v64
	v_pk_add_f32 v[66:67], v[66:67], v[68:69]
	v_pk_fma_f32 v[68:69], v[14:15], v[14:15], v[0:1] op_sel_hi:[1,1,0]
	v_mul_f32_e32 v0, v17, v17
	v_mul_f32_e32 v94, v65, v65
	v_mov_b32_e32 v69, v93
	v_pk_fma_f32 v[92:93], v[16:17], v[16:17], v[0:1] op_sel_hi:[1,1,0]
	v_mul_f32_e32 v0, v58, v58
	v_mov_b32_e32 v93, v94
	v_pk_add_f32 v[68:69], v[68:69], v[92:93]
	v_pk_mul_f32 v[92:93], v[42:43], v[42:43]
	v_pk_add_f32 v[66:67], v[66:67], v[68:69]
	v_pk_mul_f32 v[68:69], v[44:45], v[44:45]
	s_mov_b32 s0, 0x358637bd
	v_pk_mov_b32 v[94:95], v[92:93], v[68:69] op_sel:[1,0]
	v_mov_b32_e32 v93, v69
	v_pk_add_f32 v[68:69], v[94:95], v[92:93]
	v_pk_mul_f32 v[92:93], v[28:29], v[28:29]
	v_pk_mul_f32 v[94:95], v[26:27], v[26:27]
	v_pk_add_f32 v[68:69], v[68:69], v[68:69] op_sel:[0,1] op_sel_hi:[1,0]
	v_pk_mov_b32 v[96:97], v[94:95], v[92:93] op_sel:[1,0]
	v_mov_b32_e32 v95, v93
	v_pk_add_f32 v[92:93], v[96:97], v[94:95]
	v_mul_f32_e32 v94, v59, v59
	v_pk_add_f32 v[92:93], v[92:93], v[92:93] op_sel:[0,1] op_sel_hi:[1,0]
	v_mov_b32_e32 v69, v0
	v_mov_b32_e32 v93, v94
	v_mul_f32_e32 v0, v11, v11
	v_mul_f32_e32 v95, v60, v60
	v_pk_add_f32 v[68:69], v[68:69], v[92:93]
	v_pk_fma_f32 v[92:93], v[10:11], v[10:11], v[0:1] op_sel_hi:[1,1,0]
	v_mul_f32_e32 v0, v13, v13
	v_mul_f32_e32 v96, v61, v61
	v_mov_b32_e32 v93, v95
	v_pk_fma_f32 v[94:95], v[12:13], v[12:13], v[0:1] op_sel_hi:[1,1,0]
	s_nop 0
	v_mov_b32_e32 v95, v96
	v_pk_add_f32 v[92:93], v[92:93], v[94:95]
	v_pk_mul_f32 v[94:95], v[38:39], v[38:39]
	v_pk_add_f32 v[68:69], v[68:69], v[92:93]
	v_mov_b32_e32 v93, v66
	v_mov_b32_e32 v92, v68
	v_mov_b32_e32 v66, v69
	v_pk_add_f32 v[66:67], v[92:93], v[66:67]
	s_nop 1
	s_waitcnt lgkmcnt(0)
	v_add_f32_dpp v66, v66, v66 quad_perm:[1,0,3,2] row_mask:0xf bank_mask:0xf
	v_add_f32_dpp v67, v67, v67 quad_perm:[1,0,3,2] row_mask:0xf bank_mask:0xf
	s_nop 1
	s_waitcnt lgkmcnt(0)
	v_add_f32_dpp v66, v66, v66 quad_perm:[2,3,0,1] row_mask:0xf bank_mask:0xf
	v_add_f32_dpp v67, v67, v67 quad_perm:[2,3,0,1] row_mask:0xf bank_mask:0xf
	s_nop 1
	s_waitcnt lgkmcnt(0)
	v_add_f32_dpp v66, v66, v66 row_half_mirror row_mask:0xf bank_mask:0xf
	v_add_f32_dpp v67, v67, v67 row_half_mirror row_mask:0xf bank_mask:0xf
	s_nop 1
	s_waitcnt lgkmcnt(0)
	v_add_f32_dpp v66, v66, v66 row_mirror row_mask:0xf bank_mask:0xf
	v_add_f32_dpp v67, v67, v67 row_mirror row_mask:0xf bank_mask:0xf
	v_mov_b32_e32 v69, v67
	v_mov_b32_e32 v68, v66
	s_nop 1
	v_permlane16_swap_b32_e32 v69, v67
	v_permlane16_swap_b32_e32 v68, v66
	v_pk_add_f32 v[66:67], v[66:67], v[68:69]
	v_mov_b32_e32 v69, v67
	v_mov_b32_e32 v68, v66
	s_nop 1
	v_permlane32_swap_b32_e32 v69, v67
	v_permlane32_swap_b32_e32 v68, v66
	v_pk_add_f32 v[66:67], v[66:67], v[68:69]
	v_mov_b64_e32 v[68:69], s[0:1]
	v_pk_fma_f32 v[66:67], v[66:67], s[60:61], v[68:69] op_sel_hi:[1,0,0]
	s_nop 0
	v_mul_f32_e32 v0, 0x4b800000, v67
	v_cmp_gt_f32_e64 s[0:1], s40, v67
	v_cmp_gt_f32_e32 vcc, s40, v66
	s_nop 0
	v_cndmask_b32_e64 v0, v67, v0, s[0:1]
	v_rsq_f32_e32 v0, v0
	s_nop 0
	v_mul_f32_e32 v67, 0x45800000, v0
	v_cndmask_b32_e64 v92, v0, v67, s[0:1]
	v_mul_f32_e32 v0, 0x4b800000, v66
	v_cndmask_b32_e32 v0, v66, v0, vcc
	v_rsq_f32_e32 v0, v0
	v_pk_mul_f32 v[48:49], v[48:49], v[92:93] op_sel_hi:[1,0]
	v_pk_mul_f32 v[46:47], v[46:47], v[92:93] op_sel_hi:[1,0]
	v_pk_mul_f32 v[30:31], v[30:31], v[92:93] op_sel_hi:[1,0]
	v_mul_f32_e32 v66, 0x45800000, v0
	v_cndmask_b32_e32 v0, v0, v66, vcc
	v_pk_mul_f32 v[66:67], v[40:41], v[40:41]
	v_pk_mul_f32 v[42:43], v[42:43], v[0:1] op_sel_hi:[1,0]
	v_pk_mov_b32 v[96:97], v[94:95], v[66:67] op_sel:[1,0]
	v_mov_b32_e32 v95, v67
	v_pk_add_f32 v[66:67], v[96:97], v[94:95]
	v_pk_mul_f32 v[94:95], v[24:25], v[24:25]
	v_pk_add_f32 v[66:67], v[66:67], v[66:67] op_sel_hi:[0,1]
	v_pk_mul_f32 v[96:97], v[22:23], v[22:23]
	v_mul_f32_e32 v66, v6, v6
	v_pk_mov_b32 v[98:99], v[96:97], v[94:95] op_sel:[1,0]
	v_mov_b32_e32 v97, v95
	v_pk_add_f32 v[94:95], v[98:99], v[96:97]
	v_pk_fma_f32 v[96:97], v[6:7], v[6:7], v[66:67] op_sel_hi:[1,1,0]
	v_mul_f32_e32 v66, v8, v8
	v_pk_add_f32 v[94:95], v[94:95], v[94:95] op_sel_hi:[0,1]
	v_pk_fma_f32 v[98:99], v[8:9], v[8:9], v[66:67] op_sel_hi:[1,1,0]
	v_mul_f32_e32 v96, v54, v54
	v_mul_f32_e32 v98, v55, v55
	v_mul_f32_e32 v94, v56, v56
	v_mul_f32_e32 v66, v57, v57
	v_pk_add_f32 v[96:97], v[96:97], v[98:99]
	v_pk_add_f32 v[66:67], v[94:95], v[66:67]
	v_pk_mul_f32 v[94:95], v[36:37], v[36:37]
	v_pk_add_f32 v[66:67], v[96:97], v[66:67]
	v_pk_mul_f32 v[96:97], v[34:35], v[34:35]
	v_pk_mul_f32 v[44:45], v[44:45], v[0:1] op_sel_hi:[1,0]
	v_pk_mov_b32 v[98:99], v[96:97], v[94:95] op_sel:[1,0]
	v_mov_b32_e32 v97, v95
	v_pk_add_f32 v[94:95], v[98:99], v[96:97]
	v_pk_mul_f32 v[96:97], v[20:21], v[20:21]
	v_pk_add_f32 v[94:95], v[94:95], v[94:95] op_sel_hi:[0,1]
	v_pk_mul_f32 v[98:99], v[18:19], v[18:19]
	v_mul_f32_e32 v94, v2, v2
	v_pk_mov_b32 v[100:101], v[98:99], v[96:97] op_sel:[1,0]
	v_mov_b32_e32 v99, v97
	v_pk_add_f32 v[96:97], v[100:101], v[98:99]
	v_pk_fma_f32 v[98:99], v[2:3], v[2:3], v[94:95] op_sel_hi:[1,1,0]
	v_mul_f32_e32 v94, v4, v4
	v_pk_add_f32 v[96:97], v[96:97], v[96:97] op_sel_hi:[0,1]
	v_pk_fma_f32 v[100:101], v[4:5], v[4:5], v[94:95] op_sel_hi:[1,1,0]
	v_mul_f32_e32 v98, v50, v50
	v_mul_f32_e32 v100, v51, v51
	v_mul_f32_e32 v94, v52, v52
	v_mul_f32_e32 v96, v53, v53
	v_pk_add_f32 v[98:99], v[98:99], v[100:101]
	v_pk_add_f32 v[94:95], v[94:95], v[96:97]
	v_mov_b32_e32 v97, v66
	v_pk_add_f32 v[94:95], v[98:99], v[94:95]
	v_lshl_add_u64 v[100:101], v[82:83], 0, s[4:5]
	v_mov_b32_e32 v96, v94
	v_mov_b32_e32 v66, v95
	v_pk_add_f32 v[66:67], v[96:97], v[66:67]
	s_nop 1
	v_lshl_add_u64 v[98:99], v[80:81], 0, s[4:5]
	v_pk_mul_f32 v[32:33], v[32:33], v[92:93] op_sel_hi:[1,0]
	v_pk_mul_f32 v[26:27], v[26:27], v[0:1] op_sel_hi:[1,0]
	v_pk_mul_f32 v[28:29], v[28:29], v[0:1] op_sel_hi:[1,0]
	s_waitcnt lgkmcnt(0)
	v_add_f32_dpp v66, v66, v66 quad_perm:[1,0,3,2] row_mask:0xf bank_mask:0xf
	v_add_f32_dpp v67, v67, v67 quad_perm:[1,0,3,2] row_mask:0xf bank_mask:0xf
	s_nop 1
	v_pk_mul_f32 v[14:15], v[14:15], v[92:93] op_sel_hi:[1,0]
	v_pk_mul_f32 v[16:17], v[16:17], v[92:93] op_sel_hi:[1,0]
	v_pk_mul_f32 v[10:11], v[10:11], v[0:1] op_sel_hi:[1,0]
	v_pk_mul_f32 v[12:13], v[12:13], v[0:1] op_sel_hi:[1,0]
	s_waitcnt lgkmcnt(0)
	v_add_f32_dpp v66, v66, v66 quad_perm:[2,3,0,1] row_mask:0xf bank_mask:0xf
	v_add_f32_dpp v67, v67, v67 quad_perm:[2,3,0,1] row_mask:0xf bank_mask:0xf
	s_nop 1
	s_waitcnt lgkmcnt(0)
	v_add_f32_dpp v66, v66, v66 row_half_mirror row_mask:0xf bank_mask:0xf
	v_add_f32_dpp v67, v67, v67 row_half_mirror row_mask:0xf bank_mask:0xf
	s_nop 1
	s_waitcnt lgkmcnt(0)
	v_add_f32_dpp v66, v66, v66 row_mirror row_mask:0xf bank_mask:0xf
	v_add_f32_dpp v67, v67, v67 row_mirror row_mask:0xf bank_mask:0xf
	v_mov_b32_e32 v95, v67
	v_mov_b32_e32 v94, v66
	s_nop 1
	v_permlane16_swap_b32_e32 v95, v67
	v_permlane16_swap_b32_e32 v94, v66
	v_pk_add_f32 v[66:67], v[66:67], v[94:95]
	v_mov_b32_e32 v95, v67
	v_mov_b32_e32 v94, v66
	s_nop 1
	v_permlane32_swap_b32_e32 v95, v67
	v_permlane32_swap_b32_e32 v94, v66
	v_pk_add_f32 v[66:67], v[66:67], v[94:95]
	s_nop 0
	v_pk_fma_f32 v[66:67], v[66:67], s[60:61], v[68:69] op_sel_hi:[1,0,0]
	s_nop 0
	v_mul_f32_e32 v68, 0x4b800000, v67
	v_cmp_gt_f32_e64 s[0:1], s40, v67
	v_cmp_gt_f32_e32 vcc, s40, v66
	s_nop 0
	v_cndmask_b32_e64 v67, v67, v68, s[0:1]
	v_rsq_f32_e32 v67, v67
	s_nop 0
	v_mul_f32_e32 v68, 0x45800000, v67
	v_cndmask_b32_e64 v96, v67, v68, s[0:1]
	v_mul_f32_e32 v67, 0x4b800000, v66
	v_cndmask_b32_e32 v66, v66, v67, vcc
	v_rsq_f32_e32 v66, v66
	s_mov_b32 s0, 0x9000000
	v_pk_mul_f32 v[38:39], v[38:39], v[96:97] op_sel_hi:[1,0]
	v_pk_mul_f32 v[40:41], v[40:41], v[96:97] op_sel_hi:[1,0]
	v_mul_f32_e32 v67, 0x45800000, v66
	v_cndmask_b32_e32 v94, v66, v67, vcc
	global_load_dwordx4 v[66:69], v[84:85], off
	global_load_dwordx4 v[102:105], v[100:101], off
	v_pk_mul_f32 v[34:35], v[34:35], v[94:95] op_sel_hi:[1,0]
	v_pk_mul_f32 v[36:37], v[36:37], v[94:95] op_sel_hi:[1,0]
	v_pk_mul_f32 v[22:23], v[22:23], v[96:97] op_sel_hi:[1,0]
	v_pk_mul_f32 v[24:25], v[24:25], v[96:97] op_sel_hi:[1,0]
	v_pk_mul_f32 v[18:19], v[18:19], v[94:95] op_sel_hi:[1,0]
	v_pk_mul_f32 v[20:21], v[20:21], v[94:95] op_sel_hi:[1,0]
	v_pk_mul_f32 v[6:7], v[6:7], v[96:97] op_sel_hi:[1,0]
	v_pk_mul_f32 v[8:9], v[8:9], v[96:97] op_sel_hi:[1,0]
	v_pk_mul_f32 v[2:3], v[2:3], v[94:95] op_sel_hi:[1,0]
	v_pk_mul_f32 v[4:5], v[4:5], v[94:95] op_sel_hi:[1,0]
	s_waitcnt vmcnt(0)
	v_pk_add_f32 v[104:105], v[104:105], 1.0 op_sel_hi:[1,0]
	v_pk_add_f32 v[106:107], v[102:103], 1.0 op_sel_hi:[1,0]
	v_pk_mul_f32 v[102:103], v[68:69], v[104:105]
	v_pk_mul_f32 v[104:105], v[66:67], v[106:107]
	global_load_dwordx4 v[66:69], v[98:99], off
	s_waitcnt vmcnt(0)
	v_pk_fma_f32 v[48:49], v[48:49], v[102:103], v[68:69]
	s_nop 0
	v_cvt_pk_bf16_f32 v107, v48, v49
	v_add_co_u32_e32 v48, vcc, s0, v90
	v_pk_fma_f32 v[46:47], v[46:47], v[104:105], v[66:67]
	s_nop 0
	v_addc_co_u32_e32 v49, vcc, 0, v91, vcc
	s_mov_b32 s0, 0x9001000
	v_cvt_pk_bf16_f32 v106, v46, v47
	v_add_co_u32_e32 v46, vcc, s0, v90
	v_pk_fma_f32 v[44:45], v[44:45], v[102:103], v[68:69]
	v_pk_fma_f32 v[42:43], v[42:43], v[104:105], v[66:67]
	v_pk_fma_f32 v[40:41], v[102:103], v[40:41], v[68:69]
	v_pk_fma_f32 v[38:39], v[104:105], v[38:39], v[66:67]
	v_pk_fma_f32 v[36:37], v[102:103], v[36:37], v[68:69]
	v_pk_fma_f32 v[34:35], v[104:105], v[34:35], v[66:67]
	v_addc_co_u32_e32 v47, vcc, 0, v91, vcc
	v_cvt_pk_bf16_f32 v42, v42, v43
	v_cvt_pk_bf16_f32 v43, v44, v45
	v_cvt_pk_bf16_f32 v38, v38, v39
	v_cvt_pk_bf16_f32 v39, v40, v41
	v_cvt_pk_bf16_f32 v34, v34, v35
	v_cvt_pk_bf16_f32 v35, v36, v37
	global_store_dwordx2 v[46:47], v[106:107], off offset:-4096
	global_store_dwordx2 v[48:49], v[42:43], off offset:2048
	global_store_dwordx2 v[46:47], v[38:39], off
	global_store_dwordx2 v[46:47], v[34:35], off offset:2048
	global_load_dwordx4 v[34:37], v[84:85], off offset:1024
	s_nop 0
	global_load_dwordx4 v[38:41], v[100:101], off offset:1024
	s_waitcnt vmcnt(0)
	v_pk_add_f32 v[40:41], v[40:41], 1.0 op_sel_hi:[1,0]
	v_pk_add_f32 v[38:39], v[38:39], 1.0 op_sel_hi:[1,0]
	v_pk_mul_f32 v[40:41], v[36:37], v[40:41]
	v_pk_mul_f32 v[38:39], v[34:35], v[38:39]
	global_load_dwordx4 v[34:37], v[98:99], off offset:1024
	s_waitcnt vmcnt(0)
	v_pk_fma_f32 v[32:33], v[32:33], v[40:41], v[36:37]
	v_pk_fma_f32 v[30:31], v[30:31], v[38:39], v[34:35]
	v_pk_fma_f32 v[28:29], v[28:29], v[40:41], v[36:37]
	v_pk_fma_f32 v[26:27], v[26:27], v[38:39], v[34:35]
	v_pk_fma_f32 v[24:25], v[24:25], v[40:41], v[36:37]
	v_pk_fma_f32 v[22:23], v[22:23], v[38:39], v[34:35]
	v_pk_fma_f32 v[20:21], v[40:41], v[20:21], v[36:37]
	v_pk_fma_f32 v[18:19], v[38:39], v[18:19], v[34:35]
	v_cvt_pk_bf16_f32 v30, v30, v31
	v_cvt_pk_bf16_f32 v31, v32, v33
	v_cvt_pk_bf16_f32 v26, v26, v27
	v_cvt_pk_bf16_f32 v27, v28, v29
	v_cvt_pk_bf16_f32 v22, v22, v23
	v_cvt_pk_bf16_f32 v23, v24, v25
	v_cvt_pk_bf16_f32 v18, v18, v19
	v_cvt_pk_bf16_f32 v19, v20, v21
	global_store_dwordx2 v[48:49], v[30:31], off offset:512
	global_store_dwordx2 v[48:49], v[26:27], off offset:2560
	global_store_dwordx2 v[46:47], v[22:23], off offset:512
	global_store_dwordx2 v[46:47], v[18:19], off offset:2560
	global_load_dwordx4 v[18:21], v[84:85], off offset:2048
	s_nop 0
	global_load_dwordx4 v[22:25], v[100:101], off offset:2048
	s_waitcnt vmcnt(0)
	v_pk_add_f32 v[24:25], v[24:25], 1.0 op_sel_hi:[1,0]
	v_pk_add_f32 v[22:23], v[22:23], 1.0 op_sel_hi:[1,0]
	v_pk_mul_f32 v[24:25], v[20:21], v[24:25]
	v_pk_mul_f32 v[22:23], v[18:19], v[22:23]
	global_load_dwordx4 v[18:21], v[98:99], off offset:2048
	s_waitcnt vmcnt(0)
	v_pk_fma_f32 v[16:17], v[16:17], v[24:25], v[20:21]
	v_pk_fma_f32 v[14:15], v[14:15], v[22:23], v[18:19]
	v_pk_fma_f32 v[12:13], v[12:13], v[24:25], v[20:21]
	v_pk_fma_f32 v[10:11], v[10:11], v[22:23], v[18:19]
	v_pk_fma_f32 v[8:9], v[8:9], v[24:25], v[20:21]
	v_pk_fma_f32 v[6:7], v[6:7], v[22:23], v[18:19]
	v_pk_fma_f32 v[4:5], v[4:5], v[24:25], v[20:21]
	v_pk_fma_f32 v[2:3], v[2:3], v[22:23], v[18:19]
	v_cvt_pk_bf16_f32 v14, v14, v15
	v_cvt_pk_bf16_f32 v15, v16, v17
	v_cvt_pk_bf16_f32 v10, v10, v11
	v_cvt_pk_bf16_f32 v11, v12, v13
	v_cvt_pk_bf16_f32 v6, v6, v7
	v_cvt_pk_bf16_f32 v7, v8, v9
	v_cvt_pk_bf16_f32 v2, v2, v3
	v_cvt_pk_bf16_f32 v3, v4, v5
	global_store_dwordx2 v[48:49], v[14:15], off offset:1024
	global_store_dwordx2 v[48:49], v[10:11], off offset:3072
	global_store_dwordx2 v[46:47], v[6:7], off offset:1024
	global_store_dwordx2 v[46:47], v[2:3], off offset:3072
	global_load_dwordx4 v[2:5], v[84:85], off offset:3072
	s_nop 0
	global_load_dwordx4 v[6:9], v[100:101], off offset:3072
	v_pk_mul_f32 v[10:11], v[62:63], v[92:93] op_sel_hi:[1,0]
	v_pk_mul_f32 v[12:13], v[64:65], v[92:93] op_sel_hi:[1,0]
	s_waitcnt vmcnt(0)
	v_pk_add_f32 v[8:9], v[8:9], 1.0 op_sel_hi:[1,0]
	v_pk_add_f32 v[6:7], v[6:7], 1.0 op_sel_hi:[1,0]
	v_pk_mul_f32 v[8:9], v[4:5], v[8:9]
	v_pk_mul_f32 v[6:7], v[2:3], v[6:7]
	global_load_dwordx4 v[2:5], v[98:99], off offset:3072
	s_waitcnt vmcnt(0)
	v_pk_fma_f32 v[12:13], v[12:13], v[8:9], v[4:5]
	v_pk_fma_f32 v[10:11], v[10:11], v[6:7], v[2:3]
	s_nop 0
	v_cvt_pk_bf16_f32 v10, v10, v11
	v_cvt_pk_bf16_f32 v11, v12, v13
	global_store_dwordx2 v[48:49], v[10:11], off offset:1536
	v_pk_mul_f32 v[10:11], v[58:59], v[0:1] op_sel_hi:[1,0]
	v_pk_mul_f32 v[12:13], v[60:61], v[0:1] op_sel_hi:[1,0]
	v_pk_fma_f32 v[10:11], v[10:11], v[6:7], v[2:3]
	v_pk_fma_f32 v[12:13], v[12:13], v[8:9], v[4:5]
	v_cvt_pk_bf16_f32 v10, v10, v11
	v_cvt_pk_bf16_f32 v11, v12, v13
	global_store_dwordx2 v[48:49], v[10:11], off offset:3584
	v_pk_mul_f32 v[10:11], v[54:55], v[96:97] op_sel_hi:[1,0]
	v_pk_mul_f32 v[12:13], v[56:57], v[96:97] op_sel_hi:[1,0]
	v_pk_fma_f32 v[10:11], v[10:11], v[6:7], v[2:3]
	v_pk_fma_f32 v[12:13], v[12:13], v[8:9], v[4:5]
	v_cvt_pk_bf16_f32 v10, v10, v11
	v_cvt_pk_bf16_f32 v11, v12, v13
	global_store_dwordx2 v[46:47], v[10:11], off offset:1536
	v_pk_mul_f32 v[10:11], v[50:51], v[94:95] op_sel_hi:[1,0]
	v_pk_mul_f32 v[12:13], v[52:53], v[94:95] op_sel_hi:[1,0]
	v_pk_fma_f32 v[2:3], v[10:11], v[6:7], v[2:3]
	v_pk_fma_f32 v[4:5], v[12:13], v[8:9], v[4:5]
	v_cvt_pk_bf16_f32 v2, v2, v3
	v_cvt_pk_bf16_f32 v3, v4, v5
	global_store_dwordx2 v[46:47], v[2:3], off offset:3584
	s_branch .LBB0_918
